# combo23: combo22 (DPP reductions also in bias_rows) + pass C: each row's four g_o LDS reads issued before its reduction chain (renamed registers), per-read waits dropped
# speedup vs baseline: 1.0181x; 1.0027x over previous
; __device__ __forceinline__ float wave_sum(float v) {
; #pragma unroll
;     for (int o = 1; o < 64; o <<= 1) v += __shfl_xor(v, o);
;     return v;
; __device__ __forceinline__ void bias_rows(const bf16_t* __restrict__ Wt, int N, const float* __restrict__ modl, int soff, float* __restrict__ bias) {
;     ...
;     for (int n = gw; n < N; n += NGW) {
;         const u32x4 w0 = *(const u32x4*)(Wt + (size_t)n * 1024 + 16 * lane), w1 = *(const u32x4*)(Wt + (size_t)n * 1024 + 16 * lane + 8);
;         float wf[16];
; #pragma unroll
;         for (int e2 = 0; e2 < 4; ++e2) { wf[2 * e2] = __uint_as_float(w0[e2] << 16); wf[2 * e2 + 1] = __uint_as_float(w0[e2] & 0xffff0000u);
;                                          wf[8 + 2 * e2] = __uint_as_float(w1[e2] << 16); wf[8 + 2 * e2 + 1] = __uint_as_float(w1[e2] & 0xffff0000u); }
; #pragma unroll
;         for (int b = 0; b < 4; ++b) { const float* sp = modl + (size_t)b * NMOD + soff + 16 * lane; float s = 0.f;
; #pragma unroll
;             for (int q = 0; q < 4; ++q) { const f32x4 sv = *(const f32x4*)(sp + 4 * q); s += (sv[0] * wf[4 * q] + sv[1] * wf[4 * q + 1]) + (sv[2] * wf[4 * q + 2] + sv[3] * wf[4 * q + 3]); }
;             s = wave_sum(s); if (lane == 0) bias[(size_t)b * N + n] = s; }
.LBB0_124:
	v_lshl_add_u64 v[70:71], s[90:91], 0, v[68:69]
	global_load_dwordx4 v[92:95], v[70:71], off offset:-16
	global_load_dwordx4 v[96:99], v[70:71], off
	s_waitcnt vmcnt(1)
	v_lshlrev_b32_e32 v86, 16, v92
	v_and_b32_e32 v90, 0xffff0000, v92
	v_and_b32_e32 v92, 0xffff0000, v93
	v_lshlrev_b32_e32 v88, 16, v93
	v_and_b32_e32 v91, 0xffff0000, v94
	v_and_b32_e32 v93, 0xffff0000, v95
	v_mul_f32_e32 v70, v1, v90
	v_mul_f32_e32 v71, v3, v92
	s_waitcnt vmcnt(0)
	v_and_b32_e32 v82, 0xffff0000, v96
	v_and_b32_e32 v84, 0xffff0000, v97
	v_lshlrev_b32_e32 v87, 16, v94
	v_lshlrev_b32_e32 v89, 16, v95
	v_mul_f32_e32 v94, v5, v91
	v_mul_f32_e32 v95, v7, v93
	v_fmac_f32_e32 v70, v0, v86
	v_fmac_f32_e32 v71, v2, v88
	v_lshlrev_b32_e32 v64, 16, v96
	v_lshlrev_b32_e32 v80, 16, v97
	v_and_b32_e32 v83, 0xffff0000, v98
	v_and_b32_e32 v85, 0xffff0000, v99
	v_mul_f32_e32 v96, v9, v82
	v_mul_f32_e32 v97, v11, v84
	v_fmac_f32_e32 v94, v4, v87
	v_fmac_f32_e32 v95, v6, v89
	v_add_f32_e32 v70, v70, v71
	s_waitcnt lgkmcnt(0)
	v_lshlrev_b32_e32 v79, 16, v98
	v_lshlrev_b32_e32 v81, 16, v99
	v_mul_f32_e32 v98, v13, v83
	v_mul_f32_e32 v99, v15, v85
	v_fmac_f32_e32 v96, v8, v64
	v_fmac_f32_e32 v97, v10, v80
	v_add_f32_e32 v71, v94, v95
	v_add_f32_e32 v70, 0, v70
	v_fmac_f32_e32 v98, v12, v79
	v_fmac_f32_e32 v99, v14, v81
	v_add_f32_e32 v94, v96, v97
	v_add_f32_e32 v70, v71, v70
	v_add_f32_e32 v70, v94, v70
	v_add_f32_e32 v71, v98, v99
	v_add_f32_e32 v70, v71, v70
	s_nop 1
	v_add_f32_dpp v70, v70, v70 quad_perm:[1,0,3,2] row_mask:0xf bank_mask:0xf
	s_nop 1
	v_add_f32_dpp v70, v70, v70 quad_perm:[2,3,0,1] row_mask:0xf bank_mask:0xf
	s_nop 1
	v_add_f32_dpp v70, v70, v70 row_half_mirror row_mask:0xf bank_mask:0xf
	s_nop 1
	v_add_f32_dpp v70, v70, v70 row_mirror row_mask:0xf bank_mask:0xf
	s_waitcnt lgkmcnt(0)
	ds_bpermute_b32 v71, v76, v70
	s_waitcnt lgkmcnt(0)
	v_add_f32_e32 v94, v70, v71
	ds_bpermute_b32 v95, v77, v94
	v_lshl_add_u64 v[70:71], s[90:91], 0, v[66:67]
	s_and_saveexec_b64 s[40:41], s[2:3]
	s_cbranch_execz .LBB0_126
	s_waitcnt lgkmcnt(0)
	v_add_f32_e32 v96, v94, v95
	v_add_co_u32_e32 v94, vcc, 0x1f100000, v70
	s_nop 1
	v_addc_co_u32_e32 v95, vcc, 0, v71, vcc
	global_store_dword v[94:95], v96, off
.LBB0_126:
	s_or_b64 exec, exec, s[40:41]
	v_mul_f32_e32 v94, v25, v90
	s_waitcnt lgkmcnt(0)
	v_mul_f32_e32 v95, v27, v92
	v_fmac_f32_e32 v94, v24, v86
	v_fmac_f32_e32 v95, v26, v88
	v_add_f32_e32 v94, v94, v95
	v_mul_f32_e32 v95, v17, v91
	v_mul_f32_e32 v96, v19, v93
	v_fmac_f32_e32 v95, v16, v87
	v_fmac_f32_e32 v96, v18, v89
	v_add_f32_e32 v94, 0, v94
	v_add_f32_e32 v95, v95, v96
	v_add_f32_e32 v94, v95, v94
	v_mul_f32_e32 v95, v21, v82
	v_mul_f32_e32 v96, v23, v84
	v_fmac_f32_e32 v95, v20, v64
	v_fmac_f32_e32 v96, v22, v80
	v_add_f32_e32 v95, v95, v96
	v_add_f32_e32 v94, v95, v94
	v_mul_f32_e32 v95, v29, v83
	v_mul_f32_e32 v96, v31, v85
	v_fmac_f32_e32 v95, v28, v79
	v_fmac_f32_e32 v96, v30, v81
	v_add_f32_e32 v95, v95, v96
	v_add_f32_e32 v94, v95, v94
	s_nop 1
	v_add_f32_dpp v94, v94, v94 quad_perm:[1,0,3,2] row_mask:0xf bank_mask:0xf
	s_nop 1
	v_add_f32_dpp v94, v94, v94 quad_perm:[2,3,0,1] row_mask:0xf bank_mask:0xf
	s_nop 1
	v_add_f32_dpp v94, v94, v94 row_half_mirror row_mask:0xf bank_mask:0xf
	s_nop 1
	v_add_f32_dpp v94, v94, v94 row_mirror row_mask:0xf bank_mask:0xf
	s_waitcnt lgkmcnt(0)
	ds_bpermute_b32 v95, v76, v94
	s_waitcnt lgkmcnt(0)
	v_add_f32_e32 v94, v94, v95
	ds_bpermute_b32 v95, v77, v94
	s_and_saveexec_b64 s[40:41], s[2:3]
	s_cbranch_execz .LBB0_128
	s_waitcnt lgkmcnt(0)
	v_add_f32_e32 v96, v94, v95
	v_add_co_u32_e32 v94, vcc, 0x1f102000, v70
	s_nop 1
	v_addc_co_u32_e32 v95, vcc, 0, v71, vcc
	global_store_dword v[94:95], v96, off
.LBB0_128:
	s_or_b64 exec, exec, s[40:41]
	v_mul_f32_e32 v94, v41, v90
	s_waitcnt lgkmcnt(0)
	v_mul_f32_e32 v95, v43, v92
	v_fmac_f32_e32 v94, v40, v86
	v_fmac_f32_e32 v95, v42, v88
	v_add_f32_e32 v94, v94, v95
	v_mul_f32_e32 v95, v33, v91
	v_mul_f32_e32 v96, v35, v93
	v_fmac_f32_e32 v95, v32, v87
	v_fmac_f32_e32 v96, v34, v89
	v_add_f32_e32 v94, 0, v94
	v_add_f32_e32 v95, v95, v96
	v_add_f32_e32 v94, v95, v94
	v_mul_f32_e32 v95, v37, v82
	v_mul_f32_e32 v96, v39, v84
	v_fmac_f32_e32 v95, v36, v64
	v_fmac_f32_e32 v96, v38, v80
	v_add_f32_e32 v95, v95, v96
	v_add_f32_e32 v94, v95, v94
	v_mul_f32_e32 v95, v45, v83
	v_mul_f32_e32 v96, v47, v85
	v_fmac_f32_e32 v95, v44, v79
	v_fmac_f32_e32 v96, v46, v81
	v_add_f32_e32 v95, v95, v96
	v_add_f32_e32 v94, v95, v94
	s_nop 1
	v_add_f32_dpp v94, v94, v94 quad_perm:[1,0,3,2] row_mask:0xf bank_mask:0xf
	s_nop 1
	v_add_f32_dpp v94, v94, v94 quad_perm:[2,3,0,1] row_mask:0xf bank_mask:0xf
	s_nop 1
	v_add_f32_dpp v94, v94, v94 row_half_mirror row_mask:0xf bank_mask:0xf
	s_nop 1
	v_add_f32_dpp v94, v94, v94 row_mirror row_mask:0xf bank_mask:0xf
	s_waitcnt lgkmcnt(0)
	ds_bpermute_b32 v95, v76, v94
	s_waitcnt lgkmcnt(0)
	v_add_f32_e32 v94, v94, v95
	ds_bpermute_b32 v95, v77, v94
	s_and_saveexec_b64 s[40:41], s[2:3]
	s_cbranch_execz .LBB0_130
	s_waitcnt lgkmcnt(0)
	v_add_f32_e32 v96, v94, v95
	v_add_co_u32_e32 v94, vcc, 0x1f104000, v70
	s_nop 1
	v_addc_co_u32_e32 v95, vcc, 0, v71, vcc
	global_store_dword v[94:95], v96, off
.LBB0_130:
	s_or_b64 exec, exec, s[40:41]
	v_mul_f32_e32 v90, v57, v90
	v_fmac_f32_e32 v90, v56, v86
	v_mul_f32_e32 v86, v59, v92
	v_fmac_f32_e32 v86, v58, v88
	v_mul_f32_e32 v88, v49, v91
	v_mul_f32_e32 v82, v53, v82
	v_fmac_f32_e32 v88, v48, v87
	v_mul_f32_e32 v87, v51, v93
	v_fmac_f32_e32 v82, v52, v64
	v_mul_f32_e32 v64, v55, v84
	v_add_f32_e32 v86, v90, v86
	v_fmac_f32_e32 v87, v50, v89
	v_fmac_f32_e32 v64, v54, v80
	v_mul_f32_e32 v80, v61, v83
	v_add_f32_e32 v86, 0, v86
	v_add_f32_e32 v87, v88, v87
	v_fmac_f32_e32 v80, v60, v79
	v_mul_f32_e32 v79, v63, v85
	v_add_f32_e32 v86, v87, v86
	v_add_f32_e32 v64, v82, v64
	v_fmac_f32_e32 v79, v62, v81
	v_add_f32_e32 v64, v64, v86
	v_add_f32_e32 v79, v80, v79
	v_add_f32_e32 v64, v79, v64
	s_nop 1
	v_add_f32_dpp v64, v64, v64 quad_perm:[1,0,3,2] row_mask:0xf bank_mask:0xf
	s_nop 1
	v_add_f32_dpp v64, v64, v64 quad_perm:[2,3,0,1] row_mask:0xf bank_mask:0xf
	s_nop 1
	v_add_f32_dpp v64, v64, v64 row_half_mirror row_mask:0xf bank_mask:0xf
	s_nop 1
	v_add_f32_dpp v64, v64, v64 row_mirror row_mask:0xf bank_mask:0xf
	s_waitcnt lgkmcnt(0)
	ds_bpermute_b32 v79, v76, v64
	s_waitcnt lgkmcnt(0)
	v_add_f32_e32 v64, v64, v79
	ds_bpermute_b32 v79, v77, v64
	s_and_saveexec_b64 s[40:41], s[2:3]
	s_cbranch_execz .LBB0_123
	v_add_co_u32_e32 v70, vcc, 0x1f106000, v70
	s_waitcnt lgkmcnt(0)
	v_add_f32_e32 v64, v64, v79
	v_addc_co_u32_e32 v71, vcc, 0, v71, vcc
	global_store_dword v[70:71], v64, off
	s_branch .LBB0_123

; __device__ __forceinline__ void bias_rows(const bf16_t* __restrict__ Wt, int N, const float* __restrict__ modl, int soff, float* __restrict__ bias) {
;     ...
;     for (int n = gw; n < N; n += NGW) {
;         const u32x4 w0 = *(const u32x4*)(Wt + (size_t)n * 1024 + 16 * lane), w1 = *(const u32x4*)(Wt + (size_t)n * 1024 + 16 * lane + 8);
;         float wf[16];
; #pragma unroll
;         for (int e2 = 0; e2 < 4; ++e2) { wf[2 * e2] = __uint_as_float(w0[e2] << 16); wf[2 * e2 + 1] = __uint_as_float(w0[e2] & 0xffff0000u);
;                                          wf[8 + 2 * e2] = __uint_as_float(w1[e2] << 16); wf[8 + 2 * e2 + 1] = __uint_as_float(w1[e2] & 0xffff0000u); }
; #pragma unroll
;         for (int b = 0; b < 4; ++b) { const float* sp = modl + (size_t)b * NMOD + soff + 16 * lane; float s = 0.f;
; #pragma unroll
;             for (int q = 0; q < 4; ++q) { const f32x4 sv = *(const f32x4*)(sp + 4 * q); s += (sv[0] * wf[4 * q] + sv[1] * wf[4 * q + 1]) + (sv[2] * wf[4 * q + 2] + sv[3] * wf[4 * q + 3]); }
;             s = wave_sum(s); if (lane == 0) bias[(size_t)b * N + n] = s; }
.LBB0_135:
	v_lshl_add_u64 v[70:71], s[90:91], 0, v[68:69]
	v_add_co_u32_e32 v80, vcc, 0x6a0000, v70
	s_nop 1
	v_addc_co_u32_e32 v81, vcc, 0, v71, vcc
	global_load_dwordx4 v[92:95], v[80:81], off
	v_lshl_add_u64 v[70:71], v[70:71], 0, s[26:27]
	global_load_dwordx4 v[96:99], v[70:71], off offset:16
	s_waitcnt vmcnt(1)
	v_lshlrev_b32_e32 v86, 16, v92
	v_and_b32_e32 v90, 0xffff0000, v92
	v_and_b32_e32 v92, 0xffff0000, v93
	v_lshlrev_b32_e32 v88, 16, v93
	v_and_b32_e32 v91, 0xffff0000, v94
	v_and_b32_e32 v93, 0xffff0000, v95
	v_mul_f32_e32 v70, v9, v90
	v_mul_f32_e32 v71, v11, v92
	s_waitcnt vmcnt(0)
	v_and_b32_e32 v82, 0xffff0000, v96
	v_and_b32_e32 v84, 0xffff0000, v97
	v_lshlrev_b32_e32 v87, 16, v94
	v_lshlrev_b32_e32 v89, 16, v95
	v_mul_f32_e32 v94, v1, v91
	v_mul_f32_e32 v95, v3, v93
	v_fmac_f32_e32 v70, v8, v86
	v_fmac_f32_e32 v71, v10, v88
	v_lshlrev_b32_e32 v64, 16, v96
	v_lshlrev_b32_e32 v80, 16, v97
	v_and_b32_e32 v83, 0xffff0000, v98
	v_and_b32_e32 v85, 0xffff0000, v99
	v_mul_f32_e32 v96, v5, v82
	v_mul_f32_e32 v97, v7, v84
	v_fmac_f32_e32 v94, v0, v87
	v_fmac_f32_e32 v95, v2, v89
	v_add_f32_e32 v70, v70, v71
	s_waitcnt lgkmcnt(0)
	v_lshlrev_b32_e32 v79, 16, v98
	v_lshlrev_b32_e32 v81, 16, v99
	v_mul_f32_e32 v98, v13, v83
	v_mul_f32_e32 v99, v15, v85
	v_fmac_f32_e32 v96, v4, v64
	v_fmac_f32_e32 v97, v6, v80
	v_add_f32_e32 v71, v94, v95
	v_add_f32_e32 v70, 0, v70
	v_fmac_f32_e32 v98, v12, v79
	v_fmac_f32_e32 v99, v14, v81
	v_add_f32_e32 v94, v96, v97
	v_add_f32_e32 v70, v71, v70
	v_add_f32_e32 v70, v94, v70
	v_add_f32_e32 v71, v98, v99
	v_add_f32_e32 v70, v71, v70
	s_nop 1
	v_add_f32_dpp v70, v70, v70 quad_perm:[1,0,3,2] row_mask:0xf bank_mask:0xf
	s_nop 1
	v_add_f32_dpp v70, v70, v70 quad_perm:[2,3,0,1] row_mask:0xf bank_mask:0xf
	s_nop 1
	v_add_f32_dpp v70, v70, v70 row_half_mirror row_mask:0xf bank_mask:0xf
	s_nop 1
	v_add_f32_dpp v70, v70, v70 row_mirror row_mask:0xf bank_mask:0xf
	s_waitcnt lgkmcnt(0)
	ds_bpermute_b32 v71, v76, v70
	s_waitcnt lgkmcnt(0)
	v_add_f32_e32 v94, v70, v71
	ds_bpermute_b32 v95, v77, v94
	v_lshl_add_u64 v[70:71], s[90:91], 0, v[66:67]
	s_and_saveexec_b64 s[34:35], s[2:3]
	s_cbranch_execz .LBB0_137
	s_waitcnt lgkmcnt(0)
	v_add_f32_e32 v96, v94, v95
	v_add_co_u32_e32 v94, vcc, 0x1f110000, v70
	s_nop 1
	v_addc_co_u32_e32 v95, vcc, 0, v71, vcc
	global_store_dword v[94:95], v96, off
.LBB0_137:
	s_or_b64 exec, exec, s[34:35]
	v_mul_f32_e32 v94, v25, v90
	s_waitcnt lgkmcnt(0)
	v_mul_f32_e32 v95, v27, v92
	v_fmac_f32_e32 v94, v24, v86
	v_fmac_f32_e32 v95, v26, v88
	v_add_f32_e32 v94, v94, v95
	v_mul_f32_e32 v95, v17, v91
	v_mul_f32_e32 v96, v19, v93
	v_fmac_f32_e32 v95, v16, v87
	v_fmac_f32_e32 v96, v18, v89
	v_add_f32_e32 v94, 0, v94
	v_add_f32_e32 v95, v95, v96
	v_add_f32_e32 v94, v95, v94
	v_mul_f32_e32 v95, v21, v82
	v_mul_f32_e32 v96, v23, v84
	v_fmac_f32_e32 v95, v20, v64
	v_fmac_f32_e32 v96, v22, v80
	v_add_f32_e32 v95, v95, v96
	v_add_f32_e32 v94, v95, v94
	v_mul_f32_e32 v95, v29, v83
	v_mul_f32_e32 v96, v31, v85
	v_fmac_f32_e32 v95, v28, v79
	v_fmac_f32_e32 v96, v30, v81
	v_add_f32_e32 v95, v95, v96
	v_add_f32_e32 v94, v95, v94
	s_nop 1
	v_add_f32_dpp v94, v94, v94 quad_perm:[1,0,3,2] row_mask:0xf bank_mask:0xf
	s_nop 1
	v_add_f32_dpp v94, v94, v94 quad_perm:[2,3,0,1] row_mask:0xf bank_mask:0xf
	s_nop 1
	v_add_f32_dpp v94, v94, v94 row_half_mirror row_mask:0xf bank_mask:0xf
	s_nop 1
	v_add_f32_dpp v94, v94, v94 row_mirror row_mask:0xf bank_mask:0xf
	s_waitcnt lgkmcnt(0)
	ds_bpermute_b32 v95, v76, v94
	s_waitcnt lgkmcnt(0)
	v_add_f32_e32 v94, v94, v95
	ds_bpermute_b32 v95, v77, v94
	s_and_saveexec_b64 s[34:35], s[2:3]
	s_cbranch_execz .LBB0_139
	s_waitcnt lgkmcnt(0)
	v_add_f32_e32 v96, v94, v95
	v_add_co_u32_e32 v94, vcc, 0x1f114000, v70
	s_nop 1
	v_addc_co_u32_e32 v95, vcc, 0, v71, vcc
	global_store_dword v[94:95], v96, off
.LBB0_139:
	s_or_b64 exec, exec, s[34:35]
	v_mul_f32_e32 v94, v41, v90
	s_waitcnt lgkmcnt(0)
	v_mul_f32_e32 v95, v43, v92
	v_fmac_f32_e32 v94, v40, v86
	v_fmac_f32_e32 v95, v42, v88
	v_add_f32_e32 v94, v94, v95
	v_mul_f32_e32 v95, v33, v91
	v_mul_f32_e32 v96, v35, v93
	v_fmac_f32_e32 v95, v32, v87
	v_fmac_f32_e32 v96, v34, v89
	v_add_f32_e32 v94, 0, v94
	v_add_f32_e32 v95, v95, v96
	v_add_f32_e32 v94, v95, v94
	v_mul_f32_e32 v95, v37, v82
	v_mul_f32_e32 v96, v39, v84
	v_fmac_f32_e32 v95, v36, v64
	v_fmac_f32_e32 v96, v38, v80
	v_add_f32_e32 v95, v95, v96
	v_add_f32_e32 v94, v95, v94
	v_mul_f32_e32 v95, v45, v83
	v_mul_f32_e32 v96, v47, v85
	v_fmac_f32_e32 v95, v44, v79
	v_fmac_f32_e32 v96, v46, v81
	v_add_f32_e32 v95, v95, v96
	v_add_f32_e32 v94, v95, v94
	s_nop 1
	v_add_f32_dpp v94, v94, v94 quad_perm:[1,0,3,2] row_mask:0xf bank_mask:0xf
	s_nop 1
	v_add_f32_dpp v94, v94, v94 quad_perm:[2,3,0,1] row_mask:0xf bank_mask:0xf
	s_nop 1
	v_add_f32_dpp v94, v94, v94 row_half_mirror row_mask:0xf bank_mask:0xf
	s_nop 1
	v_add_f32_dpp v94, v94, v94 row_mirror row_mask:0xf bank_mask:0xf
	s_waitcnt lgkmcnt(0)
	ds_bpermute_b32 v95, v76, v94
	s_waitcnt lgkmcnt(0)
	v_add_f32_e32 v94, v94, v95
	ds_bpermute_b32 v95, v77, v94
	s_and_saveexec_b64 s[34:35], s[2:3]
	s_cbranch_execz .LBB0_141
	s_waitcnt lgkmcnt(0)
	v_add_f32_e32 v96, v94, v95
	v_add_co_u32_e32 v94, vcc, 0x1f118000, v70
	s_nop 1
	v_addc_co_u32_e32 v95, vcc, 0, v71, vcc
	global_store_dword v[94:95], v96, off
.LBB0_141:
	s_or_b64 exec, exec, s[34:35]
	v_mul_f32_e32 v90, v57, v90
	v_fmac_f32_e32 v90, v56, v86
	v_mul_f32_e32 v86, v59, v92
	v_fmac_f32_e32 v86, v58, v88
	v_mul_f32_e32 v88, v49, v91
	v_mul_f32_e32 v82, v53, v82
	v_fmac_f32_e32 v88, v48, v87
	v_mul_f32_e32 v87, v51, v93
	v_fmac_f32_e32 v82, v52, v64
	v_mul_f32_e32 v64, v55, v84
	v_add_f32_e32 v86, v90, v86
	v_fmac_f32_e32 v87, v50, v89
	v_fmac_f32_e32 v64, v54, v80
	v_mul_f32_e32 v80, v61, v83
	v_add_f32_e32 v86, 0, v86
	v_add_f32_e32 v87, v88, v87
	v_fmac_f32_e32 v80, v60, v79
	v_mul_f32_e32 v79, v63, v85
	v_add_f32_e32 v86, v87, v86
	v_add_f32_e32 v64, v82, v64
	v_fmac_f32_e32 v79, v62, v81
	v_add_f32_e32 v64, v64, v86
	v_add_f32_e32 v79, v80, v79
	v_add_f32_e32 v64, v79, v64
	s_nop 1
	v_add_f32_dpp v64, v64, v64 quad_perm:[1,0,3,2] row_mask:0xf bank_mask:0xf
	s_nop 1
	v_add_f32_dpp v64, v64, v64 quad_perm:[2,3,0,1] row_mask:0xf bank_mask:0xf
	s_nop 1
	v_add_f32_dpp v64, v64, v64 row_half_mirror row_mask:0xf bank_mask:0xf
	s_nop 1
	v_add_f32_dpp v64, v64, v64 row_mirror row_mask:0xf bank_mask:0xf
	s_waitcnt lgkmcnt(0)
	ds_bpermute_b32 v79, v76, v64
	s_waitcnt lgkmcnt(0)
	v_add_f32_e32 v64, v64, v79
	ds_bpermute_b32 v79, v77, v64
	s_and_saveexec_b64 s[34:35], s[2:3]
	s_cbranch_execz .LBB0_134
	v_add_co_u32_e32 v70, vcc, 0x1f11c000, v70
	s_waitcnt lgkmcnt(0)
	v_add_f32_e32 v64, v64, v79
	v_addc_co_u32_e32 v71, vcc, 0, v71, vcc
	global_store_dword v[70:71], v64, off
	s_branch .LBB0_134

; #define LAS __attribute__((address_space(3)))
; __device__ __forceinline__ int crow(int r, int hi) { return (r & 3) + 8 * (r >> 2) + 4 * hi; }
; __device__ __forceinline__ float bf2f(unsigned short v) { return __uint_as_float((unsigned)v << 16); }
; __device__ __forceinline__ unsigned f2bf(float f) { return pk2(f, 0.f) & 0xffffu; }
; __device__ __forceinline__ int crow(int r, int hi) { return (r & 3) + 8 * (r >> 2) + 4 * hi; }
; __device__ __forceinline__ void gla_pass_c(LAS unsigned char* ldsl, const bf16_t* __restrict__ proj, const float* __restrict__ Btab, const float* __restrict__ Gst, const float* __restrict__ gout, bf16_t* __restrict__ mixed) {
;     ...
;         { const bf16_t* gp = proj + (row0 + 32 * tb + crw) * NIN + 1024 + h * 128 + ccl * 8; u32x4 sv[8];
; #pragma unroll
;           for (int i = 0; i < 8; ++i) sv[i] = *(const u32x4*)(gp + (size_t)(4 * i) * NIN);
; #pragma unroll
;           for (int i = 0; i < 8; ++i) *(LAS u32x4*)(Lw + (4 * i + crw) * 256 + ccl * 16) = sv[i]; }
;         float gn[4];
; #pragma unroll
;         for (int dvb = 0; dvb < 4; ++dvb) gn[dvb] = gout[32 * dvb + r];
; #pragma unroll
;         for (int i = 0; i < 16; ++i) { const int tr = crow(i, hh);
;             const float tot = half_sum32((o[0][i] * o[0][i] + o[1][i] * o[1][i]) + (o[2][i] * o[2][i] + o[3][i] * o[3][i]));
;             const float rr = __builtin_amdgcn_rsqf(tot * (1.0f / 128.0f) + EPS);
; #pragma unroll
;             for (int dvb = 0; dvb < 4; ++dvb) { const float g = bf2f(Lh[tr * 128 + 32 * dvb + r]);
;                 const float val = o[dvb][i] * rr * gn[dvb] * (g * __builtin_amdgcn_rcpf(1.0f + __expf(-g)));
;                 Lh[(32 + tr) * 128 + 32 * dvb + r] = (bf16_t)f2bf(val); } }
.LBB0_873:
	v_or3_b32 v122, s2, v110, v122
	v_lshlrev_b64 v[64:65], 12, v[122:123]
	v_lshl_add_u64 v[64:65], s[60:61], 0, v[64:65]
	v_lshlrev_b32_e32 v160, 1, v124
	v_lshl_add_u64 v[64:65], v[64:65], 0, v[160:161]
	v_mov_b32_e32 v121, v161
	v_lshl_add_u64 v[92:93], v[64:65], 0, v[120:121]
	v_add_co_u32_e32 v68, vcc, 0x4000, v92
	global_load_dwordx4 v[64:67], v[92:93], off offset:2048
	s_nop 0
	v_addc_co_u32_e32 v69, vcc, 0, v93, vcc
	v_add_co_u32_e32 v72, vcc, 0x8000, v92
	global_load_dwordx4 v[68:71], v[68:69], off offset:2048
	s_nop 0
	v_addc_co_u32_e32 v73, vcc, 0, v93, vcc
	v_add_co_u32_e32 v76, vcc, 0xc000, v92
	global_load_dwordx4 v[72:75], v[72:73], off offset:2048
	s_nop 0
	v_addc_co_u32_e32 v77, vcc, 0, v93, vcc
	v_add_co_u32_e32 v80, vcc, s51, v92
	s_mov_b32 s33, 0x18000
	s_nop 0
	v_addc_co_u32_e32 v81, vcc, 0, v93, vcc
	v_add_co_u32_e32 v84, vcc, s52, v92
	global_load_dwordx4 v[76:79], v[76:77], off offset:2048
	s_nop 0
	v_addc_co_u32_e32 v85, vcc, 0, v93, vcc
	v_add_co_u32_e32 v88, vcc, s33, v92
	global_load_dwordx4 v[80:83], v[80:81], off offset:2048
	s_nop 0
	v_addc_co_u32_e32 v89, vcc, 0, v93, vcc
	s_mov_b32 s2, 0x1c000
	global_load_dwordx4 v[84:87], v[84:85], off offset:2048
	v_add_co_u32_e32 v92, vcc, s2, v92
	global_load_dwordx4 v[88:91], v[88:89], off offset:2048
	s_nop 0
	v_addc_co_u32_e32 v93, vcc, 0, v93, vcc
	global_load_dwordx4 v[92:95], v[92:93], off offset:2048
	s_movk_i32 s2, 0x2000
	s_mov_b32 s42, 0x8000
	s_waitcnt vmcnt(7)
	ds_write_b128 v140, v[64:67]
	s_waitcnt vmcnt(6)
	ds_write_b128 v140, v[68:71] offset:1024
	s_waitcnt vmcnt(5)
	ds_write_b128 v140, v[72:75] offset:2048
	s_waitcnt vmcnt(4)
	ds_write_b128 v140, v[76:79] offset:3072
	s_waitcnt vmcnt(3)
	ds_write_b128 v140, v[80:83] offset:4096
	s_waitcnt vmcnt(2)
	ds_write_b128 v140, v[84:87] offset:5120
	s_waitcnt vmcnt(1)
	ds_write_b128 v140, v[88:91] offset:6144
	s_waitcnt vmcnt(0)
	ds_write_b128 v140, v[92:95] offset:7168
	v_mul_f32_e32 v64, v16, v16
	v_mul_f32_e32 v65, v32, v32
	v_fmac_f32_e32 v64, v0, v0
	v_fmac_f32_e32 v65, v48, v48
	v_add_f32_e32 v64, v64, v65
	ds_read_u16 v144, v138
	ds_read_u16 v145, v138 offset:64
	ds_read_u16 v146, v138 offset:128
	ds_read_u16 v147, v138 offset:192
	s_nop 1
	v_add_f32_dpp v64, v64, v64 quad_perm:[1,0,3,2] row_mask:0xf bank_mask:0xf
	s_nop 1
	v_add_f32_dpp v64, v64, v64 quad_perm:[2,3,0,1] row_mask:0xf bank_mask:0xf
	s_nop 1
	v_add_f32_dpp v64, v64, v64 row_half_mirror row_mask:0xf bank_mask:0xf
	s_nop 1
	v_add_f32_dpp v64, v64, v64 row_mirror row_mask:0xf bank_mask:0xf
	s_waitcnt lgkmcnt(0)
	ds_bpermute_b32 v65, v137, v64
	s_waitcnt lgkmcnt(0)
	v_add_f32_e32 v64, v64, v65
	v_fmamk_f32 v64, v64, 0x3c000000, v199
	v_rsq_f32_e32 v64, v64
	v_lshlrev_b32_e32 v65, 16, v144
	v_mul_f32_e32 v66, 0xbfb8aa3b, v65
	v_exp_f32_e32 v66, v66
	v_mul_f32_e32 v0, v0, v64
	v_mul_f32_e32 v0, v113, v0
	v_mul_f32_e32 v16, v16, v64
	v_add_f32_e32 v66, 1.0, v66
	v_rcp_f32_e32 v66, v66
	v_mul_f32_e32 v16, v130, v16
	v_mul_f32_e32 v65, v66, v65
	v_mul_f32_e32 v0, v0, v65
	v_cvt_pk_bf16_f32 v0, v0, s0
	ds_write_b16 v138, v0 offset:8192
	v_lshlrev_b32_e32 v0, 16, v145
	v_mul_f32_e32 v65, 0xbfb8aa3b, v0
	v_exp_f32_e32 v65, v65
	s_nop 0
	v_add_f32_e32 v65, 1.0, v65
	v_rcp_f32_e32 v65, v65
	s_nop 0
	v_mul_f32_e32 v0, v65, v0
	v_mul_f32_e32 v0, v16, v0
	v_cvt_pk_bf16_f32 v0, v0, s0
	ds_write_b16 v138, v0 offset:8256
	v_mul_f32_e32 v16, v48, v64
	v_mul_f32_e32 v16, v131, v16
	v_lshlrev_b32_e32 v0, 16, v146
	v_mul_f32_e32 v48, 0xbfb8aa3b, v0
	v_exp_f32_e32 v48, v48
	s_nop 0
	v_add_f32_e32 v48, 1.0, v48
	v_rcp_f32_e32 v48, v48
	s_nop 0
	v_mul_f32_e32 v0, v48, v0
	v_mul_f32_e32 v0, v16, v0
	v_cvt_pk_bf16_f32 v0, v0, s0
	ds_write_b16 v138, v0 offset:8320
	v_mul_f32_e32 v16, v32, v64
	v_mul_f32_e32 v16, v132, v16
	v_lshlrev_b32_e32 v0, 16, v147
	v_mul_f32_e32 v32, 0xbfb8aa3b, v0
	v_exp_f32_e32 v32, v32
	s_nop 0
	v_add_f32_e32 v32, 1.0, v32
	v_rcp_f32_e32 v32, v32
	s_nop 0
	v_mul_f32_e32 v0, v32, v0
	v_mul_f32_e32 v0, v16, v0
	v_cvt_pk_bf16_f32 v0, v0, s0
	ds_write_b16 v138, v0 offset:8384
	v_mul_f32_e32 v0, v17, v17
	v_mul_f32_e32 v16, v33, v33
	v_fmac_f32_e32 v0, v1, v1
	v_fmac_f32_e32 v16, v49, v49
	v_add_f32_e32 v0, v0, v16
	ds_read_u16 v144, v138 offset:256
	ds_read_u16 v145, v138 offset:320
	ds_read_u16 v146, v138 offset:384
	ds_read_u16 v147, v138 offset:448
	s_nop 1
	v_add_f32_dpp v0, v0, v0 quad_perm:[1,0,3,2] row_mask:0xf bank_mask:0xf
	s_nop 1
	v_add_f32_dpp v0, v0, v0 quad_perm:[2,3,0,1] row_mask:0xf bank_mask:0xf
	s_nop 1
	v_add_f32_dpp v0, v0, v0 row_half_mirror row_mask:0xf bank_mask:0xf
	s_nop 1
	v_add_f32_dpp v0, v0, v0 row_mirror row_mask:0xf bank_mask:0xf
	s_waitcnt lgkmcnt(0)
	ds_bpermute_b32 v16, v137, v0
	s_waitcnt lgkmcnt(0)
; __device__ __forceinline__ int crow(int r, int hi) { return (r & 3) + 8 * (r >> 2) + 4 * hi; }
; __device__ __forceinline__ float bf2f(unsigned short v) { return __uint_as_float((unsigned)v << 16); }
; __device__ __forceinline__ unsigned f2bf(float f) { return pk2(f, 0.f) & 0xffffu; }
; __device__ __forceinline__ int crow(int r, int hi) { return (r & 3) + 8 * (r >> 2) + 4 * hi; }
; __device__ __forceinline__ void gla_pass_c(LAS unsigned char* ldsl, const bf16_t* __restrict__ proj, const float* __restrict__ Btab, const float* __restrict__ Gst, const float* __restrict__ gout, bf16_t* __restrict__ mixed) {
;     ...
;         for (int i = 0; i < 16; ++i) { const int tr = crow(i, hh);
;             const float tot = half_sum32((o[0][i] * o[0][i] + o[1][i] * o[1][i]) + (o[2][i] * o[2][i] + o[3][i] * o[3][i]));
;             const float rr = __builtin_amdgcn_rsqf(tot * (1.0f / 128.0f) + EPS);
; #pragma unroll
;             for (int dvb = 0; dvb < 4; ++dvb) { const float g = bf2f(Lh[tr * 128 + 32 * dvb + r]);
;                 const float val = o[dvb][i] * rr * gn[dvb] * (g * __builtin_amdgcn_rcpf(1.0f + __expf(-g)));
;                 Lh[(32 + tr) * 128 + 32 * dvb + r] = (bf16_t)f2bf(val); } }
	v_add_f32_e32 v0, v0, v16
	v_fmamk_f32 v0, v0, 0x3c000000, v199
	v_rsq_f32_e32 v0, v0
	v_lshlrev_b32_e32 v16, 16, v144
	v_mul_f32_e32 v32, 0xbfb8aa3b, v16
	v_exp_f32_e32 v32, v32
	v_mul_f32_e32 v1, v1, v0
	v_mul_f32_e32 v1, v113, v1
	v_add_f32_e32 v32, 1.0, v32
	v_rcp_f32_e32 v32, v32
	s_nop 0
	v_mul_f32_e32 v16, v32, v16
	v_mul_f32_e32 v1, v1, v16
	v_cvt_pk_bf16_f32 v1, v1, s0
	ds_write_b16 v138, v1 offset:8448
	v_mul_f32_e32 v16, v17, v0
	v_mul_f32_e32 v16, v130, v16
	v_lshlrev_b32_e32 v1, 16, v145
	v_mul_f32_e32 v17, 0xbfb8aa3b, v1
	v_exp_f32_e32 v17, v17
	s_nop 0
	v_add_f32_e32 v17, 1.0, v17
	v_rcp_f32_e32 v17, v17
	s_nop 0
	v_mul_f32_e32 v1, v17, v1
	v_mul_f32_e32 v1, v16, v1
	v_cvt_pk_bf16_f32 v1, v1, s0
	ds_write_b16 v138, v1 offset:8512
	v_mul_f32_e32 v16, v49, v0
	v_mul_f32_e32 v16, v131, v16
	v_mul_f32_e32 v0, v33, v0
	v_mul_f32_e32 v0, v132, v0
	v_lshlrev_b32_e32 v1, 16, v146
	v_mul_f32_e32 v17, 0xbfb8aa3b, v1
	v_exp_f32_e32 v17, v17
	s_nop 0
	v_add_f32_e32 v17, 1.0, v17
	v_rcp_f32_e32 v17, v17
	s_nop 0
	v_mul_f32_e32 v1, v17, v1
	v_mul_f32_e32 v1, v16, v1
	v_cvt_pk_bf16_f32 v1, v1, s0
	ds_write_b16 v138, v1 offset:8576
	v_lshlrev_b32_e32 v1, 16, v147
	v_mul_f32_e32 v16, 0xbfb8aa3b, v1
	v_exp_f32_e32 v16, v16
	s_nop 0
	v_add_f32_e32 v16, 1.0, v16
	v_rcp_f32_e32 v16, v16
	s_nop 0
	v_mul_f32_e32 v1, v16, v1
	v_mul_f32_e32 v0, v0, v1
	v_cvt_pk_bf16_f32 v0, v0, s0
	ds_write_b16 v138, v0 offset:8640
	v_mul_f32_e32 v0, v18, v18
	v_mul_f32_e32 v1, v34, v34
	v_fmac_f32_e32 v0, v2, v2
	v_fmac_f32_e32 v1, v50, v50
	v_add_f32_e32 v0, v0, v1
	ds_read_u16 v144, v138 offset:512
	ds_read_u16 v145, v138 offset:576
	ds_read_u16 v146, v138 offset:640
	ds_read_u16 v147, v138 offset:704
	s_nop 1
	v_add_f32_dpp v0, v0, v0 quad_perm:[1,0,3,2] row_mask:0xf bank_mask:0xf
	s_nop 1
	v_add_f32_dpp v0, v0, v0 quad_perm:[2,3,0,1] row_mask:0xf bank_mask:0xf
	s_nop 1
	v_add_f32_dpp v0, v0, v0 row_half_mirror row_mask:0xf bank_mask:0xf
	s_nop 1
	v_add_f32_dpp v0, v0, v0 row_mirror row_mask:0xf bank_mask:0xf
	s_waitcnt lgkmcnt(0)
	ds_bpermute_b32 v1, v137, v0
	s_waitcnt lgkmcnt(0)
	v_add_f32_e32 v0, v0, v1
	v_fmamk_f32 v0, v0, 0x3c000000, v199
	v_rsq_f32_e32 v0, v0
	v_lshlrev_b32_e32 v1, 16, v144
	v_mul_f32_e32 v16, 0xbfb8aa3b, v1
	v_exp_f32_e32 v16, v16
	v_mul_f32_e32 v2, v2, v0
	v_mul_f32_e32 v2, v113, v2
	v_add_f32_e32 v16, 1.0, v16
	v_rcp_f32_e32 v16, v16
	s_nop 0
	v_mul_f32_e32 v1, v16, v1
	v_mul_f32_e32 v1, v2, v1
	v_cvt_pk_bf16_f32 v1, v1, s0
	ds_write_b16 v138, v1 offset:8704
	v_mul_f32_e32 v2, v18, v0
	v_mul_f32_e32 v2, v130, v2
	v_lshlrev_b32_e32 v1, 16, v145
	v_mul_f32_e32 v16, 0xbfb8aa3b, v1
	v_exp_f32_e32 v16, v16
	s_nop 0
	v_add_f32_e32 v16, 1.0, v16
	v_rcp_f32_e32 v16, v16
	s_nop 0
	v_mul_f32_e32 v1, v16, v1
	v_mul_f32_e32 v1, v2, v1
	v_cvt_pk_bf16_f32 v1, v1, s0
	ds_write_b16 v138, v1 offset:8768
	v_mul_f32_e32 v2, v50, v0
	v_mul_f32_e32 v2, v131, v2
	v_mul_f32_e32 v0, v34, v0
	v_mul_f32_e32 v0, v132, v0
	v_lshlrev_b32_e32 v1, 16, v146
	v_mul_f32_e32 v16, 0xbfb8aa3b, v1
	v_exp_f32_e32 v16, v16
	s_nop 0
	v_add_f32_e32 v16, 1.0, v16
	v_rcp_f32_e32 v16, v16
	s_nop 0
	v_mul_f32_e32 v1, v16, v1
	v_mul_f32_e32 v1, v2, v1
	v_cvt_pk_bf16_f32 v1, v1, s0
	ds_write_b16 v138, v1 offset:8832
	v_lshlrev_b32_e32 v1, 16, v147
	v_mul_f32_e32 v2, 0xbfb8aa3b, v1
	v_exp_f32_e32 v2, v2
	s_nop 0
	v_add_f32_e32 v2, 1.0, v2
	v_rcp_f32_e32 v2, v2
	s_nop 0
	v_mul_f32_e32 v1, v2, v1
	v_mul_f32_e32 v0, v0, v1
	v_cvt_pk_bf16_f32 v0, v0, s0
	ds_write_b16 v138, v0 offset:8896
	v_mul_f32_e32 v0, v19, v19
	v_mul_f32_e32 v1, v35, v35
	v_fmac_f32_e32 v0, v3, v3
	v_fmac_f32_e32 v1, v51, v51
	v_add_f32_e32 v0, v0, v1
	ds_read_u16 v144, v138 offset:768
	ds_read_u16 v145, v138 offset:832
	ds_read_u16 v146, v138 offset:896
	ds_read_u16 v147, v138 offset:960
	s_nop 1
	v_add_f32_dpp v0, v0, v0 quad_perm:[1,0,3,2] row_mask:0xf bank_mask:0xf
	s_nop 1
	v_add_f32_dpp v0, v0, v0 quad_perm:[2,3,0,1] row_mask:0xf bank_mask:0xf
	s_nop 1
	v_add_f32_dpp v0, v0, v0 row_half_mirror row_mask:0xf bank_mask:0xf
	s_nop 1
	v_add_f32_dpp v0, v0, v0 row_mirror row_mask:0xf bank_mask:0xf
	s_waitcnt lgkmcnt(0)
	ds_bpermute_b32 v1, v137, v0
	s_waitcnt lgkmcnt(0)
	v_add_f32_e32 v0, v0, v1
	v_fmamk_f32 v0, v0, 0x3c000000, v199
	v_rsq_f32_e32 v0, v0
	v_lshlrev_b32_e32 v1, 16, v144
	v_mul_f32_e32 v2, v3, v0
	v_mul_f32_e32 v3, 0xbfb8aa3b, v1
	v_exp_f32_e32 v3, v3
	v_mul_f32_e32 v2, v113, v2
	v_add_f32_e32 v3, 1.0, v3
	v_rcp_f32_e32 v3, v3
	s_nop 0
	v_mul_f32_e32 v1, v3, v1
	v_mul_f32_e32 v1, v2, v1
	v_cvt_pk_bf16_f32 v1, v1, s0
	ds_write_b16 v138, v1 offset:8960
	v_mul_f32_e32 v2, v19, v0
	v_mul_f32_e32 v2, v130, v2
	v_lshlrev_b32_e32 v1, 16, v145
	v_mul_f32_e32 v3, 0xbfb8aa3b, v1
	v_exp_f32_e32 v3, v3
	s_nop 0
	v_add_f32_e32 v3, 1.0, v3
	v_rcp_f32_e32 v3, v3
	s_nop 0
	v_mul_f32_e32 v1, v3, v1
	v_mul_f32_e32 v1, v2, v1
	v_cvt_pk_bf16_f32 v1, v1, s0
	ds_write_b16 v138, v1 offset:9024
	v_mul_f32_e32 v2, v51, v0
	v_mul_f32_e32 v2, v131, v2
	v_mul_f32_e32 v0, v35, v0
	v_mul_f32_e32 v0, v132, v0
	v_lshlrev_b32_e32 v1, 16, v146
	v_mul_f32_e32 v3, 0xbfb8aa3b, v1
	v_exp_f32_e32 v3, v3
	s_nop 0
	v_add_f32_e32 v3, 1.0, v3
	v_rcp_f32_e32 v3, v3
	s_nop 0
	v_mul_f32_e32 v1, v3, v1
	v_mul_f32_e32 v1, v2, v1
	v_cvt_pk_bf16_f32 v1, v1, s0
	ds_write_b16 v138, v1 offset:9088
	v_lshlrev_b32_e32 v1, 16, v147
	v_mul_f32_e32 v2, 0xbfb8aa3b, v1
	v_exp_f32_e32 v2, v2
	s_nop 0
	v_add_f32_e32 v2, 1.0, v2
	v_rcp_f32_e32 v2, v2
	s_nop 0
	v_mul_f32_e32 v1, v2, v1
	v_mul_f32_e32 v0, v0, v1
	v_cvt_pk_bf16_f32 v0, v0, s0
	ds_write_b16 v138, v0 offset:9152
	v_mul_f32_e32 v0, v20, v20
	v_mul_f32_e32 v1, v36, v36
	v_fmac_f32_e32 v0, v4, v4
	v_fmac_f32_e32 v1, v52, v52
	v_add_f32_e32 v0, v0, v1
	ds_read_u16 v144, v138 offset:2048
	ds_read_u16 v145, v138 offset:2112
	ds_read_u16 v146, v138 offset:2176
	ds_read_u16 v147, v138 offset:2240
	s_nop 1
	v_add_f32_dpp v0, v0, v0 quad_perm:[1,0,3,2] row_mask:0xf bank_mask:0xf
	s_nop 1
	v_add_f32_dpp v0, v0, v0 quad_perm:[2,3,0,1] row_mask:0xf bank_mask:0xf
	s_nop 1
	v_add_f32_dpp v0, v0, v0 row_half_mirror row_mask:0xf bank_mask:0xf
	s_nop 1
	v_add_f32_dpp v0, v0, v0 row_mirror row_mask:0xf bank_mask:0xf
	s_waitcnt lgkmcnt(0)
; __device__ __forceinline__ int crow(int r, int hi) { return (r & 3) + 8 * (r >> 2) + 4 * hi; }
; __device__ __forceinline__ float bf2f(unsigned short v) { return __uint_as_float((unsigned)v << 16); }
; __device__ __forceinline__ unsigned f2bf(float f) { return pk2(f, 0.f) & 0xffffu; }
; __device__ __forceinline__ int crow(int r, int hi) { return (r & 3) + 8 * (r >> 2) + 4 * hi; }
; __device__ __forceinline__ void gla_pass_c(LAS unsigned char* ldsl, const bf16_t* __restrict__ proj, const float* __restrict__ Btab, const float* __restrict__ Gst, const float* __restrict__ gout, bf16_t* __restrict__ mixed) {
;     ...
;         for (int i = 0; i < 16; ++i) { const int tr = crow(i, hh);
;             const float tot = half_sum32((o[0][i] * o[0][i] + o[1][i] * o[1][i]) + (o[2][i] * o[2][i] + o[3][i] * o[3][i]));
;             const float rr = __builtin_amdgcn_rsqf(tot * (1.0f / 128.0f) + EPS);
; #pragma unroll
;             for (int dvb = 0; dvb < 4; ++dvb) { const float g = bf2f(Lh[tr * 128 + 32 * dvb + r]);
;                 const float val = o[dvb][i] * rr * gn[dvb] * (g * __builtin_amdgcn_rcpf(1.0f + __expf(-g)));
;                 Lh[(32 + tr) * 128 + 32 * dvb + r] = (bf16_t)f2bf(val); } }
	ds_bpermute_b32 v1, v137, v0
	s_waitcnt lgkmcnt(0)
	v_add_f32_e32 v0, v0, v1
	v_fmamk_f32 v0, v0, 0x3c000000, v199
	v_rsq_f32_e32 v0, v0
	v_lshlrev_b32_e32 v1, 16, v144
	v_mul_f32_e32 v3, 0xbfb8aa3b, v1
	v_exp_f32_e32 v3, v3
	v_mul_f32_e32 v2, v4, v0
	v_mul_f32_e32 v2, v113, v2
	v_add_f32_e32 v3, 1.0, v3
	v_rcp_f32_e32 v3, v3
	s_nop 0
	v_mul_f32_e32 v1, v3, v1
	v_mul_f32_e32 v1, v2, v1
	v_cvt_pk_bf16_f32 v1, v1, s0
	ds_write_b16 v138, v1 offset:10240
	v_mul_f32_e32 v2, v20, v0
	v_mul_f32_e32 v2, v130, v2
	v_lshlrev_b32_e32 v1, 16, v145
	v_mul_f32_e32 v3, 0xbfb8aa3b, v1
	v_exp_f32_e32 v3, v3
	s_nop 0
	v_add_f32_e32 v3, 1.0, v3
	v_rcp_f32_e32 v3, v3
	s_nop 0
	v_mul_f32_e32 v1, v3, v1
	v_mul_f32_e32 v1, v2, v1
	v_cvt_pk_bf16_f32 v1, v1, s0
	ds_write_b16 v138, v1 offset:10304
	v_mul_f32_e32 v2, v52, v0
	v_mul_f32_e32 v2, v131, v2
	v_mul_f32_e32 v0, v36, v0
	v_mul_f32_e32 v0, v132, v0
	v_lshlrev_b32_e32 v1, 16, v146
	v_mul_f32_e32 v3, 0xbfb8aa3b, v1
	v_exp_f32_e32 v3, v3
	s_nop 0
	v_add_f32_e32 v3, 1.0, v3
	v_rcp_f32_e32 v3, v3
	s_nop 0
	v_mul_f32_e32 v1, v3, v1
	v_mul_f32_e32 v1, v2, v1
	v_cvt_pk_bf16_f32 v1, v1, s0
	ds_write_b16 v138, v1 offset:10368
	v_lshlrev_b32_e32 v1, 16, v147
	v_mul_f32_e32 v2, 0xbfb8aa3b, v1
	v_exp_f32_e32 v2, v2
	s_nop 0
	v_add_f32_e32 v2, 1.0, v2
	v_rcp_f32_e32 v2, v2
	s_nop 0
	v_mul_f32_e32 v1, v2, v1
	v_mul_f32_e32 v0, v0, v1
	v_cvt_pk_bf16_f32 v0, v0, s0
	ds_write_b16 v138, v0 offset:10432
	v_mul_f32_e32 v0, v21, v21
	v_mul_f32_e32 v1, v37, v37
	v_fmac_f32_e32 v0, v5, v5
	v_fmac_f32_e32 v1, v53, v53
	v_add_f32_e32 v0, v0, v1
	ds_read_u16 v144, v138 offset:2304
	ds_read_u16 v145, v138 offset:2368
	ds_read_u16 v146, v138 offset:2432
	ds_read_u16 v147, v138 offset:2496
	s_nop 1
	v_add_f32_dpp v0, v0, v0 quad_perm:[1,0,3,2] row_mask:0xf bank_mask:0xf
	s_nop 1
	v_add_f32_dpp v0, v0, v0 quad_perm:[2,3,0,1] row_mask:0xf bank_mask:0xf
	s_nop 1
	v_add_f32_dpp v0, v0, v0 row_half_mirror row_mask:0xf bank_mask:0xf
	s_nop 1
	v_add_f32_dpp v0, v0, v0 row_mirror row_mask:0xf bank_mask:0xf
	s_waitcnt lgkmcnt(0)
	ds_bpermute_b32 v1, v137, v0
	s_waitcnt lgkmcnt(0)
	v_add_f32_e32 v0, v0, v1
	v_fmamk_f32 v0, v0, 0x3c000000, v199
	v_rsq_f32_e32 v0, v0
	v_lshlrev_b32_e32 v1, 16, v144
	v_mul_f32_e32 v3, 0xbfb8aa3b, v1
	v_exp_f32_e32 v3, v3
	v_mul_f32_e32 v2, v5, v0
	v_mul_f32_e32 v2, v113, v2
	v_add_f32_e32 v3, 1.0, v3
	v_rcp_f32_e32 v3, v3
	s_nop 0
	v_mul_f32_e32 v1, v3, v1
	v_mul_f32_e32 v1, v2, v1
	v_cvt_pk_bf16_f32 v1, v1, s0
	ds_write_b16 v138, v1 offset:10496
	v_mul_f32_e32 v2, v21, v0
	v_mul_f32_e32 v2, v130, v2
	v_lshlrev_b32_e32 v1, 16, v145
	v_mul_f32_e32 v3, 0xbfb8aa3b, v1
	v_exp_f32_e32 v3, v3
	s_nop 0
	v_add_f32_e32 v3, 1.0, v3
	v_rcp_f32_e32 v3, v3
	s_nop 0
	v_mul_f32_e32 v1, v3, v1
	v_mul_f32_e32 v1, v2, v1
	v_cvt_pk_bf16_f32 v1, v1, s0
	ds_write_b16 v138, v1 offset:10560
	v_mul_f32_e32 v2, v53, v0
	v_mul_f32_e32 v2, v131, v2
	v_mul_f32_e32 v0, v37, v0
	v_mul_f32_e32 v0, v132, v0
	v_lshlrev_b32_e32 v1, 16, v146
	v_mul_f32_e32 v3, 0xbfb8aa3b, v1
	v_exp_f32_e32 v3, v3
	s_nop 0
	v_add_f32_e32 v3, 1.0, v3
	v_rcp_f32_e32 v3, v3
	s_nop 0
	v_mul_f32_e32 v1, v3, v1
	v_mul_f32_e32 v1, v2, v1
	v_cvt_pk_bf16_f32 v1, v1, s0
	ds_write_b16 v138, v1 offset:10624
	v_lshlrev_b32_e32 v1, 16, v147
	v_mul_f32_e32 v2, 0xbfb8aa3b, v1
	v_exp_f32_e32 v2, v2
	s_nop 0
	v_add_f32_e32 v2, 1.0, v2
	v_rcp_f32_e32 v2, v2
	s_nop 0
	v_mul_f32_e32 v1, v2, v1
	v_mul_f32_e32 v0, v0, v1
	v_cvt_pk_bf16_f32 v0, v0, s0
	ds_write_b16 v138, v0 offset:10688
	v_mul_f32_e32 v0, v22, v22
	v_mul_f32_e32 v1, v38, v38
	v_fmac_f32_e32 v0, v6, v6
	v_fmac_f32_e32 v1, v54, v54
	v_add_f32_e32 v0, v0, v1
	ds_read_u16 v144, v138 offset:2560
	ds_read_u16 v145, v138 offset:2624
	ds_read_u16 v146, v138 offset:2688
	ds_read_u16 v147, v138 offset:2752
	s_nop 1
	v_add_f32_dpp v0, v0, v0 quad_perm:[1,0,3,2] row_mask:0xf bank_mask:0xf
	s_nop 1
	v_add_f32_dpp v0, v0, v0 quad_perm:[2,3,0,1] row_mask:0xf bank_mask:0xf
	s_nop 1
	v_add_f32_dpp v0, v0, v0 row_half_mirror row_mask:0xf bank_mask:0xf
	s_nop 1
	v_add_f32_dpp v0, v0, v0 row_mirror row_mask:0xf bank_mask:0xf
	s_waitcnt lgkmcnt(0)
	ds_bpermute_b32 v1, v137, v0
	s_waitcnt lgkmcnt(0)
	v_add_f32_e32 v0, v0, v1
	v_fmamk_f32 v0, v0, 0x3c000000, v199
	v_rsq_f32_e32 v0, v0
	v_lshlrev_b32_e32 v1, 16, v144
	v_mul_f32_e32 v3, 0xbfb8aa3b, v1
	v_exp_f32_e32 v3, v3
	v_mul_f32_e32 v2, v6, v0
	v_mul_f32_e32 v2, v113, v2
	v_add_f32_e32 v3, 1.0, v3
	v_rcp_f32_e32 v3, v3
	s_nop 0
	v_mul_f32_e32 v1, v3, v1
	v_mul_f32_e32 v1, v2, v1
	v_cvt_pk_bf16_f32 v1, v1, s0
	ds_write_b16 v138, v1 offset:10752
	v_mul_f32_e32 v2, v22, v0
	v_mul_f32_e32 v2, v130, v2
	v_lshlrev_b32_e32 v1, 16, v145
	v_mul_f32_e32 v3, 0xbfb8aa3b, v1
	v_exp_f32_e32 v3, v3
	s_nop 0
	v_add_f32_e32 v3, 1.0, v3
	v_rcp_f32_e32 v3, v3
	s_nop 0
	v_mul_f32_e32 v1, v3, v1
	v_mul_f32_e32 v1, v2, v1
	v_cvt_pk_bf16_f32 v1, v1, s0
	ds_write_b16 v138, v1 offset:10816
	v_mul_f32_e32 v2, v54, v0
	v_mul_f32_e32 v2, v131, v2
	v_mul_f32_e32 v0, v38, v0
	v_mul_f32_e32 v0, v132, v0
	v_lshlrev_b32_e32 v1, 16, v146
	v_mul_f32_e32 v3, 0xbfb8aa3b, v1
	v_exp_f32_e32 v3, v3
	s_nop 0
	v_add_f32_e32 v3, 1.0, v3
	v_rcp_f32_e32 v3, v3
	s_nop 0
	v_mul_f32_e32 v1, v3, v1
	v_mul_f32_e32 v1, v2, v1
	v_cvt_pk_bf16_f32 v1, v1, s0
	ds_write_b16 v138, v1 offset:10880
	v_lshlrev_b32_e32 v1, 16, v147
	v_mul_f32_e32 v2, 0xbfb8aa3b, v1
	v_exp_f32_e32 v2, v2
	s_nop 0
	v_add_f32_e32 v2, 1.0, v2
	v_rcp_f32_e32 v2, v2
	s_nop 0
	v_mul_f32_e32 v1, v2, v1
	v_mul_f32_e32 v0, v0, v1
	v_cvt_pk_bf16_f32 v0, v0, s0
	ds_write_b16 v138, v0 offset:10944
	v_mul_f32_e32 v0, v23, v23
	v_mul_f32_e32 v1, v39, v39
	v_fmac_f32_e32 v0, v7, v7
	v_fmac_f32_e32 v1, v55, v55
	v_add_f32_e32 v0, v0, v1
	ds_read_u16 v144, v138 offset:2816
	ds_read_u16 v145, v138 offset:2880
	ds_read_u16 v146, v138 offset:2944
	ds_read_u16 v147, v138 offset:3008
	s_nop 1
	v_add_f32_dpp v0, v0, v0 quad_perm:[1,0,3,2] row_mask:0xf bank_mask:0xf
	s_nop 1
	v_add_f32_dpp v0, v0, v0 quad_perm:[2,3,0,1] row_mask:0xf bank_mask:0xf
	s_nop 1
	v_add_f32_dpp v0, v0, v0 row_half_mirror row_mask:0xf bank_mask:0xf
	s_nop 1
	v_add_f32_dpp v0, v0, v0 row_mirror row_mask:0xf bank_mask:0xf
	s_waitcnt lgkmcnt(0)
; __device__ __forceinline__ int crow(int r, int hi) { return (r & 3) + 8 * (r >> 2) + 4 * hi; }
; __device__ __forceinline__ float bf2f(unsigned short v) { return __uint_as_float((unsigned)v << 16); }
; __device__ __forceinline__ unsigned f2bf(float f) { return pk2(f, 0.f) & 0xffffu; }
; __device__ __forceinline__ int crow(int r, int hi) { return (r & 3) + 8 * (r >> 2) + 4 * hi; }
; __device__ __forceinline__ void gla_pass_c(LAS unsigned char* ldsl, const bf16_t* __restrict__ proj, const float* __restrict__ Btab, const float* __restrict__ Gst, const float* __restrict__ gout, bf16_t* __restrict__ mixed) {
;     ...
;         for (int i = 0; i < 16; ++i) { const int tr = crow(i, hh);
;             const float tot = half_sum32((o[0][i] * o[0][i] + o[1][i] * o[1][i]) + (o[2][i] * o[2][i] + o[3][i] * o[3][i]));
;             const float rr = __builtin_amdgcn_rsqf(tot * (1.0f / 128.0f) + EPS);
; #pragma unroll
;             for (int dvb = 0; dvb < 4; ++dvb) { const float g = bf2f(Lh[tr * 128 + 32 * dvb + r]);
;                 const float val = o[dvb][i] * rr * gn[dvb] * (g * __builtin_amdgcn_rcpf(1.0f + __expf(-g)));
;                 Lh[(32 + tr) * 128 + 32 * dvb + r] = (bf16_t)f2bf(val); } }
	ds_bpermute_b32 v1, v137, v0
	s_waitcnt lgkmcnt(0)
	v_add_f32_e32 v0, v0, v1
	v_fmamk_f32 v0, v0, 0x3c000000, v199
	v_rsq_f32_e32 v0, v0
	v_lshlrev_b32_e32 v1, 16, v144
	v_mul_f32_e32 v3, 0xbfb8aa3b, v1
	v_exp_f32_e32 v3, v3
	v_mul_f32_e32 v2, v7, v0
	v_mul_f32_e32 v2, v113, v2
	v_add_f32_e32 v3, 1.0, v3
	v_rcp_f32_e32 v3, v3
	s_nop 0
	v_mul_f32_e32 v1, v3, v1
	v_mul_f32_e32 v1, v2, v1
	v_cvt_pk_bf16_f32 v1, v1, s0
	ds_write_b16 v138, v1 offset:11008
	v_mul_f32_e32 v2, v23, v0
	v_mul_f32_e32 v2, v130, v2
	v_lshlrev_b32_e32 v1, 16, v145
	v_mul_f32_e32 v3, 0xbfb8aa3b, v1
	v_exp_f32_e32 v3, v3
	s_nop 0
	v_add_f32_e32 v3, 1.0, v3
	v_rcp_f32_e32 v3, v3
	s_nop 0
	v_mul_f32_e32 v1, v3, v1
	v_mul_f32_e32 v1, v2, v1
	v_cvt_pk_bf16_f32 v1, v1, s0
	ds_write_b16 v138, v1 offset:11072
	v_mul_f32_e32 v2, v55, v0
	v_mul_f32_e32 v2, v131, v2
	v_mul_f32_e32 v0, v39, v0
	v_mul_f32_e32 v0, v132, v0
	v_lshlrev_b32_e32 v1, 16, v146
	v_mul_f32_e32 v3, 0xbfb8aa3b, v1
	v_exp_f32_e32 v3, v3
	s_nop 0
	v_add_f32_e32 v3, 1.0, v3
	v_rcp_f32_e32 v3, v3
	s_nop 0
	v_mul_f32_e32 v1, v3, v1
	v_mul_f32_e32 v1, v2, v1
	v_cvt_pk_bf16_f32 v1, v1, s0
	ds_write_b16 v138, v1 offset:11136
	v_lshlrev_b32_e32 v1, 16, v147
	v_mul_f32_e32 v2, 0xbfb8aa3b, v1
	v_exp_f32_e32 v2, v2
	s_nop 0
	v_add_f32_e32 v2, 1.0, v2
	v_rcp_f32_e32 v2, v2
	s_nop 0
	v_mul_f32_e32 v1, v2, v1
	v_mul_f32_e32 v0, v0, v1
	v_cvt_pk_bf16_f32 v0, v0, s0
	ds_write_b16 v138, v0 offset:11200
	v_mul_f32_e32 v0, v24, v24
	v_mul_f32_e32 v1, v40, v40
	v_fmac_f32_e32 v0, v8, v8
	v_fmac_f32_e32 v1, v56, v56
	v_add_f32_e32 v0, v0, v1
	ds_read_u16 v144, v138 offset:4096
	ds_read_u16 v145, v138 offset:4160
	ds_read_u16 v146, v138 offset:4224
	ds_read_u16 v147, v138 offset:4288
	s_nop 1
	v_add_f32_dpp v0, v0, v0 quad_perm:[1,0,3,2] row_mask:0xf bank_mask:0xf
	s_nop 1
	v_add_f32_dpp v0, v0, v0 quad_perm:[2,3,0,1] row_mask:0xf bank_mask:0xf
	s_nop 1
	v_add_f32_dpp v0, v0, v0 row_half_mirror row_mask:0xf bank_mask:0xf
	s_nop 1
	v_add_f32_dpp v0, v0, v0 row_mirror row_mask:0xf bank_mask:0xf
	s_waitcnt lgkmcnt(0)
	ds_bpermute_b32 v1, v137, v0
	s_waitcnt lgkmcnt(0)
	v_add_f32_e32 v0, v0, v1
	v_fmamk_f32 v0, v0, 0x3c000000, v199
	v_rsq_f32_e32 v0, v0
	v_lshlrev_b32_e32 v1, 16, v144
	v_mul_f32_e32 v3, 0xbfb8aa3b, v1
	v_exp_f32_e32 v3, v3
	v_mul_f32_e32 v2, v8, v0
	v_mul_f32_e32 v2, v113, v2
	v_add_f32_e32 v3, 1.0, v3
	v_rcp_f32_e32 v3, v3
	s_nop 0
	v_mul_f32_e32 v1, v3, v1
	v_mul_f32_e32 v1, v2, v1
	v_cvt_pk_bf16_f32 v1, v1, s0
	ds_write_b16 v138, v1 offset:12288
	v_mul_f32_e32 v2, v24, v0
	v_mul_f32_e32 v2, v130, v2
	v_lshlrev_b32_e32 v1, 16, v145
	v_mul_f32_e32 v3, 0xbfb8aa3b, v1
	v_exp_f32_e32 v3, v3
	s_nop 0
	v_add_f32_e32 v3, 1.0, v3
	v_rcp_f32_e32 v3, v3
	s_nop 0
	v_mul_f32_e32 v1, v3, v1
	v_mul_f32_e32 v1, v2, v1
	v_cvt_pk_bf16_f32 v1, v1, s0
	ds_write_b16 v138, v1 offset:12352
	v_mul_f32_e32 v2, v56, v0
	v_mul_f32_e32 v2, v131, v2
	v_mul_f32_e32 v0, v40, v0
	v_mul_f32_e32 v0, v132, v0
	v_lshlrev_b32_e32 v1, 16, v146
	v_mul_f32_e32 v3, 0xbfb8aa3b, v1
	v_exp_f32_e32 v3, v3
	s_nop 0
	v_add_f32_e32 v3, 1.0, v3
	v_rcp_f32_e32 v3, v3
	s_nop 0
	v_mul_f32_e32 v1, v3, v1
	v_mul_f32_e32 v1, v2, v1
	v_cvt_pk_bf16_f32 v1, v1, s0
	ds_write_b16 v138, v1 offset:12416
	v_lshlrev_b32_e32 v1, 16, v147
	v_mul_f32_e32 v2, 0xbfb8aa3b, v1
	v_exp_f32_e32 v2, v2
	s_nop 0
	v_add_f32_e32 v2, 1.0, v2
	v_rcp_f32_e32 v2, v2
	s_nop 0
	v_mul_f32_e32 v1, v2, v1
	v_mul_f32_e32 v0, v0, v1
	v_cvt_pk_bf16_f32 v0, v0, s0
	ds_write_b16 v138, v0 offset:12480
	v_mul_f32_e32 v0, v25, v25
	v_mul_f32_e32 v1, v41, v41
	v_fmac_f32_e32 v0, v9, v9
	v_fmac_f32_e32 v1, v57, v57
	v_add_f32_e32 v0, v0, v1
	ds_read_u16 v144, v138 offset:4352
	ds_read_u16 v145, v138 offset:4416
	ds_read_u16 v146, v138 offset:4480
	ds_read_u16 v147, v138 offset:4544
	s_nop 1
	v_add_f32_dpp v0, v0, v0 quad_perm:[1,0,3,2] row_mask:0xf bank_mask:0xf
	s_nop 1
	v_add_f32_dpp v0, v0, v0 quad_perm:[2,3,0,1] row_mask:0xf bank_mask:0xf
	s_nop 1
	v_add_f32_dpp v0, v0, v0 row_half_mirror row_mask:0xf bank_mask:0xf
	s_nop 1
	v_add_f32_dpp v0, v0, v0 row_mirror row_mask:0xf bank_mask:0xf
	s_waitcnt lgkmcnt(0)
	ds_bpermute_b32 v1, v137, v0
	s_waitcnt lgkmcnt(0)
	v_add_f32_e32 v0, v0, v1
	v_fmamk_f32 v0, v0, 0x3c000000, v199
	v_rsq_f32_e32 v0, v0
	v_lshlrev_b32_e32 v1, 16, v144
	v_mul_f32_e32 v3, 0xbfb8aa3b, v1
	v_exp_f32_e32 v3, v3
	v_mul_f32_e32 v2, v9, v0
	v_mul_f32_e32 v2, v113, v2
	v_add_f32_e32 v3, 1.0, v3
	v_rcp_f32_e32 v3, v3
	s_nop 0
	v_mul_f32_e32 v1, v3, v1
	v_mul_f32_e32 v1, v2, v1
	v_cvt_pk_bf16_f32 v1, v1, s0
	ds_write_b16 v138, v1 offset:12544
	v_mul_f32_e32 v2, v25, v0
	v_mul_f32_e32 v2, v130, v2
	v_lshlrev_b32_e32 v1, 16, v145
	v_mul_f32_e32 v3, 0xbfb8aa3b, v1
	v_exp_f32_e32 v3, v3
	s_nop 0
	v_add_f32_e32 v3, 1.0, v3
	v_rcp_f32_e32 v3, v3
	s_nop 0
	v_mul_f32_e32 v1, v3, v1
	v_mul_f32_e32 v1, v2, v1
	v_cvt_pk_bf16_f32 v1, v1, s0
	ds_write_b16 v138, v1 offset:12608
	v_mul_f32_e32 v2, v57, v0
	v_mul_f32_e32 v2, v131, v2
	v_mul_f32_e32 v0, v41, v0
	v_mul_f32_e32 v0, v132, v0
	v_lshlrev_b32_e32 v1, 16, v146
	v_mul_f32_e32 v3, 0xbfb8aa3b, v1
	v_exp_f32_e32 v3, v3
	s_nop 0
	v_add_f32_e32 v3, 1.0, v3
	v_rcp_f32_e32 v3, v3
	s_nop 0
	v_mul_f32_e32 v1, v3, v1
	v_mul_f32_e32 v1, v2, v1
	v_cvt_pk_bf16_f32 v1, v1, s0
	ds_write_b16 v138, v1 offset:12672
	v_lshlrev_b32_e32 v1, 16, v147
	v_mul_f32_e32 v2, 0xbfb8aa3b, v1
	v_exp_f32_e32 v2, v2
	s_nop 0
	v_add_f32_e32 v2, 1.0, v2
	v_rcp_f32_e32 v2, v2
	s_nop 0
	v_mul_f32_e32 v1, v2, v1
	v_mul_f32_e32 v0, v0, v1
	v_cvt_pk_bf16_f32 v0, v0, s0
	ds_write_b16 v138, v0 offset:12736
	v_mul_f32_e32 v0, v26, v26
	v_mul_f32_e32 v1, v42, v42
	v_fmac_f32_e32 v0, v10, v10
	v_fmac_f32_e32 v1, v58, v58
	v_add_f32_e32 v0, v0, v1
	ds_read_u16 v144, v138 offset:4608
	ds_read_u16 v145, v138 offset:4672
	ds_read_u16 v146, v138 offset:4736
	ds_read_u16 v147, v138 offset:4800
	s_nop 1
	v_add_f32_dpp v0, v0, v0 quad_perm:[1,0,3,2] row_mask:0xf bank_mask:0xf
	s_nop 1
	v_add_f32_dpp v0, v0, v0 quad_perm:[2,3,0,1] row_mask:0xf bank_mask:0xf
	s_nop 1
	v_add_f32_dpp v0, v0, v0 row_half_mirror row_mask:0xf bank_mask:0xf
	s_nop 1
	v_add_f32_dpp v0, v0, v0 row_mirror row_mask:0xf bank_mask:0xf
	s_waitcnt lgkmcnt(0)
; __device__ __forceinline__ int crow(int r, int hi) { return (r & 3) + 8 * (r >> 2) + 4 * hi; }
; __device__ __forceinline__ float bf2f(unsigned short v) { return __uint_as_float((unsigned)v << 16); }
; __device__ __forceinline__ unsigned f2bf(float f) { return pk2(f, 0.f) & 0xffffu; }
; __device__ __forceinline__ int crow(int r, int hi) { return (r & 3) + 8 * (r >> 2) + 4 * hi; }
; __device__ __forceinline__ void gla_pass_c(LAS unsigned char* ldsl, const bf16_t* __restrict__ proj, const float* __restrict__ Btab, const float* __restrict__ Gst, const float* __restrict__ gout, bf16_t* __restrict__ mixed) {
;     ...
;         for (int i = 0; i < 16; ++i) { const int tr = crow(i, hh);
;             const float tot = half_sum32((o[0][i] * o[0][i] + o[1][i] * o[1][i]) + (o[2][i] * o[2][i] + o[3][i] * o[3][i]));
;             const float rr = __builtin_amdgcn_rsqf(tot * (1.0f / 128.0f) + EPS);
; #pragma unroll
;             for (int dvb = 0; dvb < 4; ++dvb) { const float g = bf2f(Lh[tr * 128 + 32 * dvb + r]);
;                 const float val = o[dvb][i] * rr * gn[dvb] * (g * __builtin_amdgcn_rcpf(1.0f + __expf(-g)));
;                 Lh[(32 + tr) * 128 + 32 * dvb + r] = (bf16_t)f2bf(val); } }
	ds_bpermute_b32 v1, v137, v0
	s_waitcnt lgkmcnt(0)
	v_add_f32_e32 v0, v0, v1
	v_fmamk_f32 v0, v0, 0x3c000000, v199
	v_rsq_f32_e32 v0, v0
	v_lshlrev_b32_e32 v1, 16, v144
	v_mul_f32_e32 v3, 0xbfb8aa3b, v1
	v_exp_f32_e32 v3, v3
	v_mul_f32_e32 v2, v10, v0
	v_mul_f32_e32 v2, v113, v2
	v_add_f32_e32 v3, 1.0, v3
	v_rcp_f32_e32 v3, v3
	s_nop 0
	v_mul_f32_e32 v1, v3, v1
	v_mul_f32_e32 v1, v2, v1
	v_cvt_pk_bf16_f32 v1, v1, s0
	ds_write_b16 v138, v1 offset:12800
	v_mul_f32_e32 v2, v26, v0
	v_mul_f32_e32 v2, v130, v2
	v_lshlrev_b32_e32 v1, 16, v145
	v_mul_f32_e32 v3, 0xbfb8aa3b, v1
	v_exp_f32_e32 v3, v3
	s_nop 0
	v_add_f32_e32 v3, 1.0, v3
	v_rcp_f32_e32 v3, v3
	s_nop 0
	v_mul_f32_e32 v1, v3, v1
	v_mul_f32_e32 v1, v2, v1
	v_cvt_pk_bf16_f32 v1, v1, s0
	ds_write_b16 v138, v1 offset:12864
	v_mul_f32_e32 v2, v58, v0
	v_mul_f32_e32 v2, v131, v2
	v_mul_f32_e32 v0, v42, v0
	v_mul_f32_e32 v0, v132, v0
	v_lshlrev_b32_e32 v1, 16, v146
	v_mul_f32_e32 v3, 0xbfb8aa3b, v1
	v_exp_f32_e32 v3, v3
	s_nop 0
	v_add_f32_e32 v3, 1.0, v3
	v_rcp_f32_e32 v3, v3
	s_nop 0
	v_mul_f32_e32 v1, v3, v1
	v_mul_f32_e32 v1, v2, v1
	v_cvt_pk_bf16_f32 v1, v1, s0
	ds_write_b16 v138, v1 offset:12928
	v_lshlrev_b32_e32 v1, 16, v147
	v_mul_f32_e32 v2, 0xbfb8aa3b, v1
	v_exp_f32_e32 v2, v2
	s_nop 0
	v_add_f32_e32 v2, 1.0, v2
	v_rcp_f32_e32 v2, v2
	s_nop 0
	v_mul_f32_e32 v1, v2, v1
	v_mul_f32_e32 v0, v0, v1
	v_cvt_pk_bf16_f32 v0, v0, s0
	ds_write_b16 v138, v0 offset:12992
	v_mul_f32_e32 v0, v27, v27
	v_mul_f32_e32 v1, v43, v43
	v_fmac_f32_e32 v0, v11, v11
	v_fmac_f32_e32 v1, v59, v59
	v_add_f32_e32 v0, v0, v1
	ds_read_u16 v144, v138 offset:4864
	ds_read_u16 v145, v138 offset:4928
	ds_read_u16 v146, v138 offset:4992
	ds_read_u16 v147, v138 offset:5056
	s_nop 1
	v_add_f32_dpp v0, v0, v0 quad_perm:[1,0,3,2] row_mask:0xf bank_mask:0xf
	s_nop 1
	v_add_f32_dpp v0, v0, v0 quad_perm:[2,3,0,1] row_mask:0xf bank_mask:0xf
	s_nop 1
	v_add_f32_dpp v0, v0, v0 row_half_mirror row_mask:0xf bank_mask:0xf
	s_nop 1
	v_add_f32_dpp v0, v0, v0 row_mirror row_mask:0xf bank_mask:0xf
	s_waitcnt lgkmcnt(0)
	ds_bpermute_b32 v1, v137, v0
	s_waitcnt lgkmcnt(0)
	v_add_f32_e32 v0, v0, v1
	v_fmamk_f32 v0, v0, 0x3c000000, v199
	v_rsq_f32_e32 v0, v0
	v_lshlrev_b32_e32 v1, 16, v144
	v_mul_f32_e32 v3, 0xbfb8aa3b, v1
	v_exp_f32_e32 v3, v3
	v_mul_f32_e32 v2, v11, v0
	v_mul_f32_e32 v2, v113, v2
	v_add_f32_e32 v3, 1.0, v3
	v_rcp_f32_e32 v3, v3
	s_nop 0
	v_mul_f32_e32 v1, v3, v1
	v_mul_f32_e32 v1, v2, v1
	v_cvt_pk_bf16_f32 v1, v1, s0
	ds_write_b16 v138, v1 offset:13056
	v_mul_f32_e32 v2, v27, v0
	v_mul_f32_e32 v2, v130, v2
	v_lshlrev_b32_e32 v1, 16, v145
	v_mul_f32_e32 v3, 0xbfb8aa3b, v1
	v_exp_f32_e32 v3, v3
	s_nop 0
	v_add_f32_e32 v3, 1.0, v3
	v_rcp_f32_e32 v3, v3
	s_nop 0
	v_mul_f32_e32 v1, v3, v1
	v_mul_f32_e32 v1, v2, v1
	v_cvt_pk_bf16_f32 v1, v1, s0
	ds_write_b16 v138, v1 offset:13120
	v_mul_f32_e32 v2, v59, v0
	v_mul_f32_e32 v2, v131, v2
	v_mul_f32_e32 v0, v43, v0
	v_mul_f32_e32 v0, v132, v0
	v_lshlrev_b32_e32 v1, 16, v146
	v_mul_f32_e32 v3, 0xbfb8aa3b, v1
	v_exp_f32_e32 v3, v3
	s_nop 0
	v_add_f32_e32 v3, 1.0, v3
	v_rcp_f32_e32 v3, v3
	s_nop 0
	v_mul_f32_e32 v1, v3, v1
	v_mul_f32_e32 v1, v2, v1
	v_cvt_pk_bf16_f32 v1, v1, s0
	ds_write_b16 v138, v1 offset:13184
	v_lshlrev_b32_e32 v1, 16, v147
	v_mul_f32_e32 v2, 0xbfb8aa3b, v1
	v_exp_f32_e32 v2, v2
	s_nop 0
	v_add_f32_e32 v2, 1.0, v2
	v_rcp_f32_e32 v2, v2
	s_nop 0
	v_mul_f32_e32 v1, v2, v1
	v_mul_f32_e32 v0, v0, v1
	v_cvt_pk_bf16_f32 v0, v0, s0
	ds_write_b16 v138, v0 offset:13248
	v_mul_f32_e32 v0, v28, v28
	v_mul_f32_e32 v1, v44, v44
	v_fmac_f32_e32 v0, v12, v12
	v_fmac_f32_e32 v1, v60, v60
	v_add_f32_e32 v0, v0, v1
	ds_read_u16 v144, v138 offset:6144
	ds_read_u16 v145, v138 offset:6208
	ds_read_u16 v146, v138 offset:6272
	ds_read_u16 v147, v138 offset:6336
	s_nop 1
	v_add_f32_dpp v0, v0, v0 quad_perm:[1,0,3,2] row_mask:0xf bank_mask:0xf
	s_nop 1
	v_add_f32_dpp v0, v0, v0 quad_perm:[2,3,0,1] row_mask:0xf bank_mask:0xf
	s_nop 1
	v_add_f32_dpp v0, v0, v0 row_half_mirror row_mask:0xf bank_mask:0xf
	s_nop 1
	v_add_f32_dpp v0, v0, v0 row_mirror row_mask:0xf bank_mask:0xf
	s_waitcnt lgkmcnt(0)
	ds_bpermute_b32 v1, v137, v0
	s_waitcnt lgkmcnt(0)
	v_add_f32_e32 v0, v0, v1
	v_fmamk_f32 v0, v0, 0x3c000000, v199
	v_rsq_f32_e32 v0, v0
	v_lshlrev_b32_e32 v1, 16, v144
	v_mul_f32_e32 v3, 0xbfb8aa3b, v1
	v_exp_f32_e32 v3, v3
	v_mul_f32_e32 v2, v12, v0
	v_mul_f32_e32 v2, v113, v2
	v_add_f32_e32 v3, 1.0, v3
	v_rcp_f32_e32 v3, v3
	s_nop 0
	v_mul_f32_e32 v1, v3, v1
	v_mul_f32_e32 v1, v2, v1
	v_cvt_pk_bf16_f32 v1, v1, s0
	ds_write_b16 v138, v1 offset:14336
	v_mul_f32_e32 v2, v28, v0
	v_mul_f32_e32 v2, v130, v2
	v_lshlrev_b32_e32 v1, 16, v145
	v_mul_f32_e32 v3, 0xbfb8aa3b, v1
	v_exp_f32_e32 v3, v3
	s_nop 0
	v_add_f32_e32 v3, 1.0, v3
	v_rcp_f32_e32 v3, v3
	s_nop 0
	v_mul_f32_e32 v1, v3, v1
	v_mul_f32_e32 v1, v2, v1
	v_cvt_pk_bf16_f32 v1, v1, s0
	ds_write_b16 v138, v1 offset:14400
	v_mul_f32_e32 v2, v60, v0
	v_mul_f32_e32 v2, v131, v2
	v_mul_f32_e32 v0, v44, v0
	v_mul_f32_e32 v0, v132, v0
	v_lshlrev_b32_e32 v1, 16, v146
	v_mul_f32_e32 v3, 0xbfb8aa3b, v1
	v_exp_f32_e32 v3, v3
	s_nop 0
	v_add_f32_e32 v3, 1.0, v3
	v_rcp_f32_e32 v3, v3
	s_nop 0
	v_mul_f32_e32 v1, v3, v1
	v_mul_f32_e32 v1, v2, v1
	v_cvt_pk_bf16_f32 v1, v1, s0
	ds_write_b16 v138, v1 offset:14464
	v_lshlrev_b32_e32 v1, 16, v147
	v_mul_f32_e32 v2, 0xbfb8aa3b, v1
	v_exp_f32_e32 v2, v2
	s_nop 0
	v_add_f32_e32 v2, 1.0, v2
	v_rcp_f32_e32 v2, v2
	s_nop 0
	v_mul_f32_e32 v1, v2, v1
	v_mul_f32_e32 v0, v0, v1
	v_cvt_pk_bf16_f32 v0, v0, s0
	ds_write_b16 v138, v0 offset:14528
	v_mul_f32_e32 v0, v29, v29
	v_mul_f32_e32 v1, v45, v45
	v_fmac_f32_e32 v0, v13, v13
	v_fmac_f32_e32 v1, v61, v61
	v_add_f32_e32 v0, v0, v1
	ds_read_u16 v144, v138 offset:6400
	ds_read_u16 v145, v138 offset:6464
	ds_read_u16 v146, v138 offset:6528
	ds_read_u16 v147, v138 offset:6592
	s_nop 1
	v_add_f32_dpp v0, v0, v0 quad_perm:[1,0,3,2] row_mask:0xf bank_mask:0xf
	s_nop 1
	v_add_f32_dpp v0, v0, v0 quad_perm:[2,3,0,1] row_mask:0xf bank_mask:0xf
	s_nop 1
	v_add_f32_dpp v0, v0, v0 row_half_mirror row_mask:0xf bank_mask:0xf
	s_nop 1
	v_add_f32_dpp v0, v0, v0 row_mirror row_mask:0xf bank_mask:0xf
	s_waitcnt lgkmcnt(0)
; __device__ __forceinline__ int crow(int r, int hi) { return (r & 3) + 8 * (r >> 2) + 4 * hi; }
; __device__ __forceinline__ float bf2f(unsigned short v) { return __uint_as_float((unsigned)v << 16); }
; __device__ __forceinline__ unsigned f2bf(float f) { return pk2(f, 0.f) & 0xffffu; }
; __device__ __forceinline__ int crow(int r, int hi) { return (r & 3) + 8 * (r >> 2) + 4 * hi; }
; __device__ __forceinline__ void gla_pass_c(LAS unsigned char* ldsl, const bf16_t* __restrict__ proj, const float* __restrict__ Btab, const float* __restrict__ Gst, const float* __restrict__ gout, bf16_t* __restrict__ mixed) {
;     ...
;         for (int i = 0; i < 16; ++i) { const int tr = crow(i, hh);
;             const float tot = half_sum32((o[0][i] * o[0][i] + o[1][i] * o[1][i]) + (o[2][i] * o[2][i] + o[3][i] * o[3][i]));
;             const float rr = __builtin_amdgcn_rsqf(tot * (1.0f / 128.0f) + EPS);
; #pragma unroll
;             for (int dvb = 0; dvb < 4; ++dvb) { const float g = bf2f(Lh[tr * 128 + 32 * dvb + r]);
;                 const float val = o[dvb][i] * rr * gn[dvb] * (g * __builtin_amdgcn_rcpf(1.0f + __expf(-g)));
;                 Lh[(32 + tr) * 128 + 32 * dvb + r] = (bf16_t)f2bf(val); } }
	ds_bpermute_b32 v1, v137, v0
	s_waitcnt lgkmcnt(0)
	v_add_f32_e32 v0, v0, v1
	v_fmamk_f32 v0, v0, 0x3c000000, v199
	v_rsq_f32_e32 v0, v0
	v_lshlrev_b32_e32 v1, 16, v144
	v_mul_f32_e32 v3, 0xbfb8aa3b, v1
	v_exp_f32_e32 v3, v3
	v_mul_f32_e32 v2, v13, v0
	v_mul_f32_e32 v2, v113, v2
	v_add_f32_e32 v3, 1.0, v3
	v_rcp_f32_e32 v3, v3
	s_nop 0
	v_mul_f32_e32 v1, v3, v1
	v_mul_f32_e32 v1, v2, v1
	v_cvt_pk_bf16_f32 v1, v1, s0
	ds_write_b16 v138, v1 offset:14592
	v_mul_f32_e32 v2, v29, v0
	v_mul_f32_e32 v2, v130, v2
	v_lshlrev_b32_e32 v1, 16, v145
	v_mul_f32_e32 v3, 0xbfb8aa3b, v1
	v_exp_f32_e32 v3, v3
	s_nop 0
	v_add_f32_e32 v3, 1.0, v3
	v_rcp_f32_e32 v3, v3
	s_nop 0
	v_mul_f32_e32 v1, v3, v1
	v_mul_f32_e32 v1, v2, v1
	v_cvt_pk_bf16_f32 v1, v1, s0
	ds_write_b16 v138, v1 offset:14656
	v_mul_f32_e32 v2, v61, v0
	v_mul_f32_e32 v2, v131, v2
	v_mul_f32_e32 v0, v45, v0
	v_mul_f32_e32 v0, v132, v0
	v_lshlrev_b32_e32 v1, 16, v146
	v_mul_f32_e32 v3, 0xbfb8aa3b, v1
	v_exp_f32_e32 v3, v3
	s_nop 0
	v_add_f32_e32 v3, 1.0, v3
	v_rcp_f32_e32 v3, v3
	s_nop 0
	v_mul_f32_e32 v1, v3, v1
	v_mul_f32_e32 v1, v2, v1
	v_cvt_pk_bf16_f32 v1, v1, s0
	ds_write_b16 v138, v1 offset:14720
	v_lshlrev_b32_e32 v1, 16, v147
	v_mul_f32_e32 v2, 0xbfb8aa3b, v1
	v_exp_f32_e32 v2, v2
	s_nop 0
	v_add_f32_e32 v2, 1.0, v2
	v_rcp_f32_e32 v2, v2
	s_nop 0
	v_mul_f32_e32 v1, v2, v1
	v_mul_f32_e32 v0, v0, v1
	v_cvt_pk_bf16_f32 v0, v0, s0
	ds_write_b16 v138, v0 offset:14784
	v_mul_f32_e32 v0, v30, v30
	v_mul_f32_e32 v1, v46, v46
	v_fmac_f32_e32 v0, v14, v14
	v_fmac_f32_e32 v1, v62, v62
	v_add_f32_e32 v0, v0, v1
	ds_read_u16 v144, v138 offset:6656
	ds_read_u16 v145, v138 offset:6720
	ds_read_u16 v146, v138 offset:6784
	ds_read_u16 v147, v138 offset:6848
	s_nop 1
	v_add_f32_dpp v0, v0, v0 quad_perm:[1,0,3,2] row_mask:0xf bank_mask:0xf
	s_nop 1
	v_add_f32_dpp v0, v0, v0 quad_perm:[2,3,0,1] row_mask:0xf bank_mask:0xf
	s_nop 1
	v_add_f32_dpp v0, v0, v0 row_half_mirror row_mask:0xf bank_mask:0xf
	s_nop 1
	v_add_f32_dpp v0, v0, v0 row_mirror row_mask:0xf bank_mask:0xf
	s_waitcnt lgkmcnt(0)
	ds_bpermute_b32 v1, v137, v0
	s_waitcnt lgkmcnt(0)
	v_add_f32_e32 v0, v0, v1
	v_fmamk_f32 v0, v0, 0x3c000000, v199
	v_rsq_f32_e32 v0, v0
	v_lshlrev_b32_e32 v1, 16, v144
	v_mul_f32_e32 v3, 0xbfb8aa3b, v1
	v_exp_f32_e32 v3, v3
	v_mul_f32_e32 v2, v14, v0
	v_mul_f32_e32 v2, v113, v2
	v_add_f32_e32 v3, 1.0, v3
	v_rcp_f32_e32 v3, v3
	s_nop 0
	v_mul_f32_e32 v1, v3, v1
	v_mul_f32_e32 v1, v2, v1
	v_cvt_pk_bf16_f32 v1, v1, s0
	ds_write_b16 v138, v1 offset:14848
	v_mul_f32_e32 v2, v30, v0
	v_mul_f32_e32 v2, v130, v2
	v_lshlrev_b32_e32 v1, 16, v145
	v_mul_f32_e32 v3, 0xbfb8aa3b, v1
	v_exp_f32_e32 v3, v3
	s_nop 0
	v_add_f32_e32 v3, 1.0, v3
	v_rcp_f32_e32 v3, v3
	s_nop 0
	v_mul_f32_e32 v1, v3, v1
	v_mul_f32_e32 v1, v2, v1
	v_cvt_pk_bf16_f32 v1, v1, s0
	ds_write_b16 v138, v1 offset:14912
	v_mul_f32_e32 v2, v62, v0
	v_mul_f32_e32 v2, v131, v2
	v_mul_f32_e32 v0, v46, v0
	v_mul_f32_e32 v0, v132, v0
	v_lshlrev_b32_e32 v1, 16, v146
	v_mul_f32_e32 v3, 0xbfb8aa3b, v1
	v_exp_f32_e32 v3, v3
	s_nop 0
	v_add_f32_e32 v3, 1.0, v3
	v_rcp_f32_e32 v3, v3
	s_nop 0
	v_mul_f32_e32 v1, v3, v1
	v_mul_f32_e32 v1, v2, v1
	v_cvt_pk_bf16_f32 v1, v1, s0
	ds_write_b16 v138, v1 offset:14976
	v_lshlrev_b32_e32 v1, 16, v147
	v_mul_f32_e32 v2, 0xbfb8aa3b, v1
	v_exp_f32_e32 v2, v2
	s_nop 0
	v_add_f32_e32 v2, 1.0, v2
	v_rcp_f32_e32 v2, v2
	s_nop 0
	v_mul_f32_e32 v1, v2, v1
	v_mul_f32_e32 v0, v0, v1
	v_cvt_pk_bf16_f32 v0, v0, s0
	ds_write_b16 v138, v0 offset:15040
	v_mul_f32_e32 v0, v31, v31
	v_mul_f32_e32 v1, v47, v47
	v_fmac_f32_e32 v0, v15, v15
	v_fmac_f32_e32 v1, v63, v63
	v_add_f32_e32 v0, v0, v1
	ds_read_u16 v144, v138 offset:6912
	ds_read_u16 v145, v138 offset:6976
	ds_read_u16 v146, v138 offset:7040
	ds_read_u16 v147, v138 offset:7104
	s_nop 1
	v_add_f32_dpp v0, v0, v0 quad_perm:[1,0,3,2] row_mask:0xf bank_mask:0xf
	s_nop 1
	v_add_f32_dpp v0, v0, v0 quad_perm:[2,3,0,1] row_mask:0xf bank_mask:0xf
	s_nop 1
	v_add_f32_dpp v0, v0, v0 row_half_mirror row_mask:0xf bank_mask:0xf
	s_nop 1
	v_add_f32_dpp v0, v0, v0 row_mirror row_mask:0xf bank_mask:0xf
	s_waitcnt lgkmcnt(0)
; #define LAS __attribute__((address_space(3)))
; __device__ __forceinline__ int crow(int r, int hi) { return (r & 3) + 8 * (r >> 2) + 4 * hi; }
; __device__ __forceinline__ float bf2f(unsigned short v) { return __uint_as_float((unsigned)v << 16); }
; __device__ __forceinline__ unsigned f2bf(float f) { return pk2(f, 0.f) & 0xffffu; }
; __device__ __forceinline__ int crow(int r, int hi) { return (r & 3) + 8 * (r >> 2) + 4 * hi; }
; __device__ __forceinline__ void gla_pass_c(LAS unsigned char* ldsl, const bf16_t* __restrict__ proj, const float* __restrict__ Btab, const float* __restrict__ Gst, const float* __restrict__ gout, bf16_t* __restrict__ mixed) {
;     ...
;         for (int i = 0; i < 16; ++i) { const int tr = crow(i, hh);
;             const float tot = half_sum32((o[0][i] * o[0][i] + o[1][i] * o[1][i]) + (o[2][i] * o[2][i] + o[3][i] * o[3][i]));
;             const float rr = __builtin_amdgcn_rsqf(tot * (1.0f / 128.0f) + EPS);
; #pragma unroll
;             for (int dvb = 0; dvb < 4; ++dvb) { const float g = bf2f(Lh[tr * 128 + 32 * dvb + r]);
;                 const float val = o[dvb][i] * rr * gn[dvb] * (g * __builtin_amdgcn_rcpf(1.0f + __expf(-g)));
;                 Lh[(32 + tr) * 128 + 32 * dvb + r] = (bf16_t)f2bf(val); } }
;         { bf16_t* mp = mixed + (row0 + 32 * tb + crw) * DM + h * 128 + ccl * 8;
; #pragma unroll
;           for (int i = 0; i < 8; ++i) *(u32x4*)(mp + (size_t)(4 * i) * DM) = *(const LAS u32x4*)(Lw + (32 + 4 * i + crw) * 256 + ccl * 16); }
;     }
	ds_bpermute_b32 v1, v137, v0
	s_waitcnt lgkmcnt(0)
	v_add_f32_e32 v0, v0, v1
	v_fmamk_f32 v0, v0, 0x3c000000, v199
	v_rsq_f32_e32 v0, v0
	v_lshlrev_b32_e32 v1, 16, v144
	v_mul_f32_e32 v3, 0xbfb8aa3b, v1
	v_exp_f32_e32 v3, v3
	v_mul_f32_e32 v2, v15, v0
	v_mul_f32_e32 v2, v113, v2
	v_add_f32_e32 v3, 1.0, v3
	v_rcp_f32_e32 v3, v3
	s_nop 0
	v_mul_f32_e32 v1, v3, v1
	v_mul_f32_e32 v1, v2, v1
	v_cvt_pk_bf16_f32 v1, v1, s0
	ds_write_b16 v138, v1 offset:15104
	v_mul_f32_e32 v2, v31, v0
	v_mul_f32_e32 v2, v130, v2
	v_lshlrev_b32_e32 v1, 16, v145
	v_mul_f32_e32 v3, 0xbfb8aa3b, v1
	v_exp_f32_e32 v3, v3
	s_nop 0
	v_add_f32_e32 v3, 1.0, v3
	v_rcp_f32_e32 v3, v3
	s_nop 0
	v_mul_f32_e32 v1, v3, v1
	v_mul_f32_e32 v1, v2, v1
	v_cvt_pk_bf16_f32 v1, v1, s0
	ds_write_b16 v138, v1 offset:15168
	v_mul_f32_e32 v2, v63, v0
	v_mul_f32_e32 v2, v131, v2
	v_mul_f32_e32 v0, v47, v0
	v_mul_f32_e32 v0, v132, v0
	v_lshlrev_b32_e32 v1, 16, v146
	v_mul_f32_e32 v3, 0xbfb8aa3b, v1
	v_exp_f32_e32 v3, v3
	s_nop 0
	v_add_f32_e32 v3, 1.0, v3
	v_rcp_f32_e32 v3, v3
	s_nop 0
	v_mul_f32_e32 v1, v3, v1
	v_mul_f32_e32 v1, v2, v1
	v_cvt_pk_bf16_f32 v1, v1, s0
	ds_write_b16 v138, v1 offset:15232
	v_lshlrev_b32_e32 v1, 16, v147
	v_mul_f32_e32 v2, 0xbfb8aa3b, v1
	v_exp_f32_e32 v2, v2
	s_nop 0
	v_add_f32_e32 v2, 1.0, v2
	v_rcp_f32_e32 v2, v2
	s_nop 0
	v_mul_f32_e32 v1, v2, v1
	v_mul_f32_e32 v0, v0, v1
	v_cvt_pk_bf16_f32 v0, v0, s0
	ds_write_b16 v138, v0 offset:15296
	v_lshlrev_b64 v[0:1], 11, v[122:123]
	v_lshl_add_u64 v[0:1], s[54:55], 0, v[0:1]
	v_lshl_add_u64 v[0:1], v[0:1], 0, v[160:161]
	v_lshl_add_u64 v[4:5], v[0:1], 0, v[120:121]
	ds_read_b128 v[0:3], v140 offset:8192
	v_add_co_u32_e32 v6, vcc, s2, v4
	s_movk_i32 s2, 0x6000
	s_nop 0
	v_addc_co_u32_e32 v7, vcc, 0, v5, vcc
	s_waitcnt lgkmcnt(0)
	global_store_dwordx4 v[4:5], v[0:3], off
	ds_read_b128 v[0:3], v140 offset:9216
	s_waitcnt lgkmcnt(0)
	global_store_dwordx4 v[6:7], v[0:3], off
	ds_read_b128 v[0:3], v140 offset:10240
	v_add_co_u32_e32 v6, vcc, s49, v4
	s_nop 1
	v_addc_co_u32_e32 v7, vcc, 0, v5, vcc
	s_waitcnt lgkmcnt(0)
	global_store_dwordx4 v[6:7], v[0:3], off
	ds_read_b128 v[0:3], v140 offset:11264
	v_add_co_u32_e32 v6, vcc, s2, v4
	s_mov_b32 s2, 0xa000
	s_nop 0
	v_addc_co_u32_e32 v7, vcc, 0, v5, vcc
	s_waitcnt lgkmcnt(0)
	global_store_dwordx4 v[6:7], v[0:3], off
	ds_read_b128 v[0:3], v140 offset:12288
	v_add_co_u32_e32 v6, vcc, s42, v4
	s_nop 1
	v_addc_co_u32_e32 v7, vcc, 0, v5, vcc
	s_waitcnt lgkmcnt(0)
	global_store_dwordx4 v[6:7], v[0:3], off
	ds_read_b128 v[0:3], v140 offset:13312
	v_add_co_u32_e32 v6, vcc, s2, v4
	s_movk_i32 s2, 0x7ff
	s_nop 0
	v_addc_co_u32_e32 v7, vcc, 0, v5, vcc
	s_waitcnt lgkmcnt(0)
	global_store_dwordx4 v[6:7], v[0:3], off
	ds_read_b128 v[0:3], v140 offset:14336
	v_add_co_u32_e32 v6, vcc, 0xc000, v4
	s_nop 1
	v_addc_co_u32_e32 v7, vcc, 0, v5, vcc
	s_waitcnt lgkmcnt(0)
	global_store_dwordx4 v[6:7], v[0:3], off
	ds_read_b128 v[0:3], v140 offset:15360
	v_add_co_u32_e32 v4, vcc, 0xe000, v4
	s_nop 1
	v_addc_co_u32_e32 v5, vcc, 0, v5, vcc
	s_waitcnt lgkmcnt(0)
	global_store_dwordx4 v[4:5], v[0:3], off
	v_cmp_lt_i32_e32 vcc, s2, v111
	s_or_b64 s[40:41], vcc, s[40:41]
	v_add_u32_e32 v0, 0x800, v111
	v_mov_b32_e32 v111, v0
	s_andn2_b64 exec, exec, s[40:41]
	s_cbranch_execz .LBB0_880
